# v92 + K-tile order rotated by row tile in the phase A / phase C GEMM loops (against L2 channel camping; f32 summation order only)
# baseline (speedup 1.0000x reference)
.LBB0_159:
	v_mov_b32_e32 v78, v133
	s_lshl_b32 s22, s2, 8
	s_bfe_u32 s32, s22, 0x30008
	s_lshl_b32 s32, s32, 15
	v_ashrrev_i32_e32 v6, 6, v78
	v_bfe_u32 v7, v78, 3, 3
	v_lshl_or_b32 v8, v6, 5, v7
	v_add_u32_e32 v0, s22, v8
	s_waitcnt lgkmcnt(0)
	v_ashrrev_i32_e32 v1, 31, v0
	v_lshlrev_b64 v[2:3], 11, v[0:1]
	v_bfe_u32 v1, v78, 4, 2
	v_readlane_b32 s0, v214, 4
	v_xor_b32_e32 v1, v1, v78
	v_readlane_b32 s1, v214, 5
	v_lshlrev_b32_e32 v1, 4, v1
	v_and_b32_e32 v64, 0x70, v1
	v_lshl_add_u64 v[2:3], s[0:1], 0, v[2:3]
	v_or_b32_e32 v1, 8, v8
	v_lshl_add_u64 v[66:67], v[2:3], 0, v[64:65]
	v_add_u32_e32 v2, s22, v1
	v_lshrrev_b32_e32 v1, 1, v1
	v_xor_b32_e32 v1, v1, v78
	v_ashrrev_i32_e32 v3, 31, v2
	v_lshlrev_b32_e32 v1, 4, v1
	v_or_b32_e32 v0, 16, v0
	v_lshlrev_b64 v[2:3], 11, v[2:3]
	v_and_b32_e32 v4, 0x70, v1
	v_ashrrev_i32_e32 v1, 31, v0
	v_lshl_add_u64 v[2:3], s[0:1], 0, v[2:3]
	v_mov_b32_e32 v5, v65
	v_lshlrev_b64 v[0:1], 11, v[0:1]
	v_lshl_add_u64 v[68:69], v[2:3], 0, v[4:5]
	v_lshl_add_u64 v[0:1], s[0:1], 0, v[0:1]
	v_or_b32_e32 v2, 24, v8
	v_lshl_add_u64 v[70:71], v[0:1], 0, v[64:65]
	v_add_u32_e32 v0, s22, v2
	v_lshrrev_b32_e32 v2, 1, v2
	v_ashrrev_i32_e32 v1, 31, v0
	v_xor_b32_e32 v2, v2, v78
	v_lshlrev_b64 v[0:1], 11, v[0:1]
	v_lshlrev_b32_e32 v2, 4, v2
	v_lshl_add_u64 v[0:1], s[0:1], 0, v[0:1]
	v_and_b32_e32 v2, 0x70, v2
	v_mov_b32_e32 v3, v65
	v_lshl_add_u64 v[72:73], v[0:1], 0, v[2:3]
	v_lshl_or_b32 v2, v6, 4, v7
	v_readlane_b32 s31, v214, 58
	v_lshlrev_b32_e32 v3, 12, v6
	v_add_u32_e32 v126, 0, v3
	v_add_u32_e32 v0, s31, v2
	v_ashrrev_i32_e32 v1, 31, v0
	v_lshlrev_b64 v[0:1], 11, v[0:1]
	s_waitcnt vmcnt(0)
	v_readfirstlane_b32 s37, v126
	v_add_u32_e32 v127, 0x400, v126
	v_lshl_add_u64 v[0:1], s[40:41], 0, v[0:1]
	v_or_b32_e32 v2, 8, v2
	s_waitcnt lgkmcnt(0)
	s_barrier
	s_mov_b32 m0, s37
	v_readfirstlane_b32 s38, v127
	v_add_u32_e32 v128, 0x800, v126
	v_lshlrev_b32_e32 v5, 11, v6
	v_and_b32_e32 v80, 1, v6
	v_lshl_add_u64 v[74:75], v[0:1], 0, v[64:65]
	v_add_u32_e32 v0, s31, v2
	v_lshrrev_b32_e32 v2, 1, v2
	global_load_lds_dwordx4 v[66:67], off
	s_mov_b32 m0, s38
	v_readfirstlane_b32 s39, v128
	v_add_u32_e32 v129, 0xc00, v126
	v_add_u32_e32 v6, 0, v5
	v_ashrrev_i32_e32 v1, 31, v0
	v_xor_b32_e32 v2, v2, v78
	global_load_lds_dwordx4 v[68:69], off
	s_mov_b32 m0, s39
	v_readfirstlane_b32 s48, v129
	v_add_u32_e32 v131, 0x8000, v6
	v_lshlrev_b64 v[0:1], 11, v[0:1]
	v_lshlrev_b32_e32 v2, 4, v2
	global_load_lds_dwordx4 v[70:71], off
	s_mov_b32 m0, s48
	v_readfirstlane_b32 s49, v131
	v_add_u32_e32 v130, 0x8400, v6
	v_lshl_add_u64 v[0:1], s[40:41], 0, v[0:1]
	v_and_b32_e32 v64, 0x70, v2
	global_load_lds_dwordx4 v[72:73], off
	s_mov_b32 m0, s49
	v_readfirstlane_b32 s53, v130
	v_add_u32_e32 v120, 0xc000, v126
	v_lshl_add_u64 v[76:77], v[0:1], 0, v[64:65]
	global_load_lds_dwordx4 v[74:75], off
	s_mov_b32 m0, s53
	s_lshr_b32 s0, s32, 15
	s_add_i32 s0, s0, 0
	s_sub_i32 s1, s0, 15
	s_cmp_ge_u32 s0, 15
	s_cselect_b32 s0, s1, s0
	s_add_i32 s0, s0, 1
	s_lshl_b32 s0, s0, 7
	s_mov_b32 s1, 0
	v_readfirstlane_b32 s28, v120
	v_add_u32_e32 v121, 0xc400, v126
	global_load_lds_dwordx4 v[76:77], off
	v_lshl_add_u64 v[0:1], v[66:67], 0, s[0:1]
	s_mov_b32 m0, s28
	v_readfirstlane_b32 s29, v121
	v_add_u32_e32 v122, 0xc800, v126
	global_load_lds_dwordx4 v[0:1], off
	v_lshl_add_u64 v[0:1], v[68:69], 0, s[0:1]
	s_mov_b32 m0, s29
	v_readfirstlane_b32 s33, v122
	v_add_u32_e32 v123, 0xcc00, v126
	global_load_lds_dwordx4 v[0:1], off
	v_lshl_add_u64 v[0:1], v[70:71], 0, s[0:1]
	s_mov_b32 m0, s33
	v_readfirstlane_b32 s34, v123
	v_add_u32_e32 v124, s85, v5
	global_load_lds_dwordx4 v[0:1], off
	v_lshl_add_u64 v[0:1], v[72:73], 0, s[0:1]
	s_mov_b32 m0, s34
	v_readfirstlane_b32 s35, v124
	v_add_u32_e32 v125, 0x14400, v6
	global_load_lds_dwordx4 v[0:1], off
	v_lshl_add_u64 v[0:1], v[74:75], 0, s[0:1]
	s_mov_b32 m0, s35
	v_readfirstlane_b32 s36, v125
	global_load_lds_dwordx4 v[0:1], off
	v_lshl_add_u64 v[0:1], v[76:77], 0, s[0:1]
	s_mov_b32 m0, s36
	v_lshrrev_b32_e32 v2, 1, v78
	v_bfe_u32 v64, v78, 5, 1
	global_load_lds_dwordx4 v[0:1], off
	v_add_u32_e32 v114, s3, v3
	v_bitop3_b32 v0, v2, v64, 7 bitop3:0x6c
	s_waitcnt vmcnt(6)
	s_lshr_b32 s46, s32, 15
	s_add_i32 s46, s46, 1
	s_sub_i32 s47, s46, 15
	s_cmp_ge_u32 s46, 15
	s_cselect_b32 s46, s47, s46
	s_add_i32 s46, s46, 1
	s_lshl_b32 s46, s46, 7
	s_mov_b32 s47, 0
	v_readfirstlane_b32 s0, v114
	v_add_u32_e32 v115, 0x400, v114
	v_lshlrev_b32_e32 v132, 4, v0
	s_waitcnt lgkmcnt(0)
	s_barrier
	v_lshl_add_u64 v[0:1], v[66:67], 0, s[46:47]
	s_mov_b32 m0, s0
	v_readfirstlane_b32 s1, v115
	v_add_u32_e32 v116, 0x800, v114
	global_load_lds_dwordx4 v[0:1], off
	v_lshl_add_u64 v[0:1], v[68:69], 0, s[46:47]
	s_mov_b32 m0, s1
	v_readfirstlane_b32 s20, v116
	v_add_u32_e32 v117, 0xc00, v114
	v_readlane_b32 s23, v212, 31
	v_and_b32_e32 v79, 31, v78
	global_load_lds_dwordx4 v[0:1], off
	v_lshl_add_u64 v[0:1], v[70:71], 0, s[46:47]
	s_mov_b32 m0, s20
	v_readfirstlane_b32 s21, v117
	v_add_u32_e32 v118, s23, v5
	v_add_u32_e32 v2, s3, v5
	v_lshlrev_b32_e32 v4, 7, v79
	global_load_lds_dwordx4 v[0:1], off
	v_lshl_add_u64 v[0:1], v[72:73], 0, s[46:47]
	s_mov_b32 m0, s21
	v_readfirstlane_b32 s23, v118
	v_add_u32_e32 v119, 0x8400, v2
	v_lshl_or_b32 v102, v80, 13, v4
	global_load_lds_dwordx4 v[0:1], off
	v_lshl_add_u64 v[0:1], v[74:75], 0, s[46:47]
	s_mov_b32 m0, s23
	v_readfirstlane_b32 s24, v119
	global_load_lds_dwordx4 v[0:1], off
	v_lshl_add_u64 v[0:1], v[76:77], 0, s[46:47]
	s_mov_b32 m0, s24
	v_add_u32_e32 v100, 0, v102
	global_load_lds_dwordx4 v[0:1], off
	v_add_u32_e32 v83, v100, v132
	v_ashrrev_i32_e32 v81, 7, v78
	ds_read_b128 a[0:3], v83 offset:32768
	ds_read_b128 a[4:7], v83 offset:36864
	v_lshl_or_b32 v134, v81, 13, v4
	v_add_u32_e32 v101, 0, v134
	v_add_u32_e32 v82, v101, v132
	ds_read_b128 a[8:11], v82
	ds_read_b128 a[12:15], v82 offset:4096
	v_lshrrev_b32_e32 v182, 6, v133
	v_or_b32_e32 v182, s32, v182
	s_nop 0
	v_readfirstlane_b32 s32, v182
	s_waitcnt lgkmcnt(1)
	v_mfma_f32_32x32x16_bf16 v[48:63], a[0:3], a[8:11], 0
	v_bfe_u32 v103, v78, 1, 3
	s_lshr_b32 s46, s32, 15
	s_add_i32 s46, s46, 2
	s_sub_i32 s47, s46, 15
	s_cmp_ge_u32 s46, 15
	s_cselect_b32 s46, s47, s46
	s_add_i32 s46, s46, 1
	s_lshl_b32 s46, s46, 7
	s_mov_b32 s47, 0
	s_nop 0
	s_add_i32 s30, 0, 0xc000
	v_or_b32_e32 v143, 0x8000, v102
	v_or_b32_e32 v144, 0x9000, v102
	v_add_u32_e32 v145, s3, v134
	s_waitcnt vmcnt(12)
	v_mfma_f32_32x32x16_bf16 v[32:47], a[4:7], a[8:11], 0
	v_lshl_or_b32 v81, v81, 6, v79
	v_mul_lo_u32 v81, v81, s26
	s_mov_b64 s[80:81], 0x200
	s_waitcnt lgkmcnt(0)
	v_mfma_f32_32x32x16_bf16 v[16:31], a[0:3], a[12:15], 0
	v_bitop3_b32 v0, v64, v103, 2 bitop3:0x36
	v_lshlrev_b32_e32 v138, 4, v0
	v_add_u32_e32 v84, v101, v138
	ds_read_b128 a[28:31], v84 offset:4096
	s_nop 0
	s_nop 0
	ds_read_b128 a[24:27], v84
	s_nop 0
	v_add_u32_e32 v85, v100, v138
	ds_read_b128 a[20:23], v85 offset:36864
	s_nop 0
	s_nop 0
	ds_read_b128 a[16:19], v85 offset:32768
	s_nop 0
	s_nop 0
	s_nop 0
	s_nop 0
	s_nop 0
	s_nop 0
	v_mfma_f32_32x32x16_bf16 v[0:15], a[4:7], a[12:15], 0
	s_nop 0
	s_waitcnt lgkmcnt(0)
	v_mfma_f32_32x32x16_bf16 v[48:63], a[16:19], a[24:27], v[48:63]
	v_mfma_f32_32x32x16_bf16 v[32:47], a[20:23], a[24:27], v[32:47]
	v_mfma_f32_32x32x16_bf16 v[16:31], a[16:19], a[28:31], v[16:31]
	v_bitop3_b32 v86, v64, v103, 4 bitop3:0x36
	v_lshlrev_b32_e32 v139, 4, v86
	v_add_u32_e32 v86, v101, v139
	ds_read_b128 a[12:15], v86 offset:4096
	s_nop 0
	s_nop 0
	ds_read_b128 a[8:11], v86
	s_nop 0
	v_add_u32_e32 v87, v100, v139
	ds_read_b128 a[4:7], v87 offset:36864
	s_nop 0
	s_nop 0
	ds_read_b128 a[0:3], v87 offset:32768
	s_nop 0
	s_nop 0
	s_nop 0
	v_mfma_f32_32x32x16_bf16 v[0:15], a[20:23], a[28:31], v[0:15]
	s_nop 0
	s_nop 0
	s_nop 0
	s_nop 0
	s_waitcnt lgkmcnt(0)
	v_mfma_f32_32x32x16_bf16 v[48:63], a[0:3], a[8:11], v[48:63]
	v_mfma_f32_32x32x16_bf16 v[32:47], a[4:7], a[8:11], v[32:47]
	v_mfma_f32_32x32x16_bf16 v[16:31], a[0:3], a[12:15], v[16:31]
	v_bitop3_b32 v88, v64, v103, 6 bitop3:0x36
	v_lshlrev_b32_e32 v142, 4, v88
	v_add_u32_e32 v88, v101, v142
	ds_read_b128 a[28:31], v88 offset:4096
	s_nop 0
	s_nop 0
	ds_read_b128 a[24:27], v88
	s_nop 0
	v_add_u32_e32 v89, v100, v142
	ds_read_b128 a[20:23], v89 offset:36864
	s_nop 0
	s_nop 0
	ds_read_b128 a[16:19], v89 offset:32768
	s_nop 0
	s_nop 0
	s_nop 0
	v_lshlrev_b32_e32 v64, 4, v64
	v_lshl_or_b32 v64, v80, 8, v64
	v_add3_u32 v64, 0, v81, v64
	v_mfma_f32_32x32x16_bf16 v[0:15], a[4:7], a[12:15], v[0:15]
	s_nop 0
	s_nop 0
	s_nop 0
	s_nop 0
	s_waitcnt lgkmcnt(0)
	v_mfma_f32_32x32x16_bf16 v[48:63], a[16:19], a[24:27], v[48:63]
	v_mfma_f32_32x32x16_bf16 v[32:47], a[20:23], a[24:27], v[32:47]
	s_waitcnt vmcnt(6)
	s_waitcnt lgkmcnt(0)
	s_barrier
	ds_read_b128 a[12:15], v82 offset:53248
	ds_read_b128 a[8:11], v82 offset:49152
	v_add_u32_e32 v90, s30, v132
	v_add_u32_e32 v92, v90, v143
	v_add_u32_e32 v90, v90, v144
	ds_read_b128 a[4:7], v90
	ds_read_b128 a[0:3], v92
	v_mfma_f32_32x32x16_bf16 v[16:31], a[16:19], a[28:31], v[16:31]
	v_lshl_add_u64 v[158:159], v[66:67], 0, s[46:47]
	s_nop 0
	v_lshl_add_u64 v[160:161], v[68:69], 0, s[46:47]
	s_nop 0
	s_nop 0
	s_nop 0
	v_lshl_add_u64 v[162:163], v[70:71], 0, s[46:47]
	s_nop 0
	v_mfma_f32_32x32x16_bf16 v[0:15], a[20:23], a[28:31], v[0:15]
	s_and_b32 m0, s32, 7
	s_lshl_b32 m0, m0, 12
	s_add_i32 m0, m0, 0x0
	s_nop 0
	global_load_lds_dwordx4 v[158:159], off
	s_nop 0
	v_lshl_add_u64 v[164:165], v[72:73], 0, s[46:47]
	s_nop 0
	s_nop 0
	s_nop 0
	v_lshl_add_u64 v[166:167], v[74:75], 0, s[46:47]
	s_nop 0
	s_nop 0
	s_nop 0
	v_lshl_add_u64 v[168:169], v[76:77], 0, s[46:47]
	s_nop 0
	s_lshr_b32 s46, s32, 15
	s_add_i32 s46, s46, 3
	s_sub_i32 s47, s46, 15
	s_cmp_ge_u32 s46, 15
	s_cselect_b32 s46, s47, s46
	s_add_i32 s46, s46, 1
	s_lshl_b32 s46, s46, 7
	s_mov_b32 s47, 0
	s_nop 0
	s_nop 0
	s_nop 0
	s_nop 0
	s_nop 0
	s_nop 0
	s_nop 0
	s_nop 0
	v_add_u32_e32 v91, s30, v138
	v_add_u32_e32 v93, v91, v143
	ds_read_b128 a[16:19], v93
	v_add_u32_e32 v91, v91, v144
	ds_read_b128 a[20:23], v91
	ds_read_b128 a[24:27], v84 offset:49152
	ds_read_b128 a[28:31], v84 offset:53248
	s_waitcnt lgkmcnt(4)
	v_mfma_f32_32x32x16_bf16 v[48:63], a[0:3], a[8:11], v[48:63]
	s_nop 0
	s_nop 0
	s_nop 0
	s_nop 0
	v_mfma_f32_32x32x16_bf16 v[32:47], a[4:7], a[8:11], v[32:47]
	v_mfma_f32_32x32x16_bf16 v[16:31], a[0:3], a[12:15], v[16:31]
	s_and_b32 m0, s32, 7
	s_lshl_b32 m0, m0, 12
	s_add_i32 m0, m0, 0x400
	s_nop 0
	global_load_lds_dwordx4 v[160:161], off
	v_mfma_f32_32x32x16_bf16 v[0:15], a[4:7], a[12:15], v[0:15]
	s_nop 0
	s_nop 0
	s_nop 0
	s_nop 0
	v_add_u32_e32 v94, s30, v139
	v_add_u32_e32 v95, v94, v143
	ds_read_b128 a[0:3], v95
	v_add_u32_e32 v94, v94, v144
	ds_read_b128 a[4:7], v94
	ds_read_b128 a[8:11], v86 offset:49152
	ds_read_b128 a[12:15], v86 offset:53248
	s_waitcnt lgkmcnt(5)
	v_mfma_f32_32x32x16_bf16 v[48:63], a[16:19], a[24:27], v[48:63]
	v_mfma_f32_32x32x16_bf16 v[32:47], a[20:23], a[24:27], v[32:47]
	s_and_b32 m0, s32, 7
	s_lshl_b32 m0, m0, 12
	s_add_i32 m0, m0, 0x800
	s_nop 0
	global_load_lds_dwordx4 v[162:163], off
	s_waitcnt lgkmcnt(4)
	v_mfma_f32_32x32x16_bf16 v[16:31], a[16:19], a[28:31], v[16:31]
	s_nop 0
	s_nop 0
	s_nop 0
	v_mfma_f32_32x32x16_bf16 v[0:15], a[20:23], a[28:31], v[0:15]
	s_nop 0
	s_nop 0
	s_nop 0
	s_nop 0
	v_add_u32_e32 v96, s30, v142
	v_add_u32_e32 v97, v96, v143
	ds_read_b128 a[16:19], v97
	v_add_u32_e32 v96, v96, v144
	ds_read_b128 a[20:23], v96
	ds_read_b128 a[24:27], v88 offset:49152
	ds_read_b128 a[28:31], v88 offset:53248
	s_waitcnt lgkmcnt(5)
	v_mfma_f32_32x32x16_bf16 v[48:63], a[0:3], a[8:11], v[48:63]
	s_and_b32 m0, s32, 7
	s_lshl_b32 m0, m0, 12
	s_add_i32 m0, m0, 0xc00
	s_nop 0
	global_load_lds_dwordx4 v[164:165], off
	v_mfma_f32_32x32x16_bf16 v[32:47], a[4:7], a[8:11], v[32:47]
	s_waitcnt lgkmcnt(4)
	v_mfma_f32_32x32x16_bf16 v[16:31], a[0:3], a[12:15], v[16:31]
	s_nop 0
	s_nop 0
	s_nop 0
	v_mfma_f32_32x32x16_bf16 v[0:15], a[4:7], a[12:15], v[0:15]
	s_and_b32 m0, s32, 7
	s_lshl_b32 m0, m0, 11
	s_add_i32 m0, m0, 0x8000
	s_nop 0
	global_load_lds_dwordx4 v[166:167], off
	s_nop 0
	s_nop 0
	s_nop 0
	s_nop 0
	s_waitcnt lgkmcnt(1)
	v_mfma_f32_32x32x16_bf16 v[48:63], a[16:19], a[24:27], v[48:63]
	v_mfma_f32_32x32x16_bf16 v[32:47], a[20:23], a[24:27], v[32:47]
	s_and_b32 m0, s32, 7
	s_lshl_b32 m0, m0, 11
	s_add_i32 m0, m0, 0x8400
	s_nop 0
	global_load_lds_dwordx4 v[168:169], off
	s_waitcnt vmcnt(6)
	s_waitcnt lgkmcnt(0)
	s_barrier
	v_add_u32_e32 v100, v145, v132
	ds_read_b128 a[8:11], v100
	v_add_u32_e32 v101, s3, v132
	v_add_u32_e32 v99, v101, v144
	ds_read_b128 a[4:7], v99
	s_nop 0
	v_add_u32_e32 v98, v101, v143
	v_or_b32_e32 v132, 0x1000, v134
	v_add_u32_e32 v101, v101, v132
	ds_read_b128 a[12:15], v101
	ds_read_b128 a[0:3], v98
	v_mfma_f32_32x32x16_bf16 v[16:31], a[16:19], a[28:31], v[16:31]
	v_lshl_add_u64 v[170:171], v[66:67], 0, s[46:47]
	s_nop 0
	v_lshl_add_u64 v[172:173], v[68:69], 0, s[46:47]
	s_nop 0
	s_nop 0
	s_nop 0
	v_lshl_add_u64 v[174:175], v[70:71], 0, s[46:47]
	s_nop 0
	v_mfma_f32_32x32x16_bf16 v[0:15], a[20:23], a[28:31], v[0:15]
	s_and_b32 m0, s32, 7
	s_lshl_b32 m0, m0, 12
	s_add_i32 m0, m0, 0xc000
	s_nop 0
	global_load_lds_dwordx4 v[170:171], off
	s_nop 0
	v_lshl_add_u64 v[176:177], v[72:73], 0, s[46:47]
	s_nop 0
	s_nop 0
	s_nop 0
	v_lshl_add_u64 v[178:179], v[74:75], 0, s[46:47]
	s_nop 0
	s_nop 0
	s_nop 0
	v_lshl_add_u64 v[180:181], v[76:77], 0, s[46:47]
	s_nop 0
	s_lshr_b32 s46, s32, 15
	s_add_i32 s46, s46, 4
	s_sub_i32 s47, s46, 15
	s_cmp_ge_u32 s46, 15
	s_cselect_b32 s46, s47, s46
	s_add_i32 s46, s46, 1
	s_lshl_b32 s46, s46, 7
	s_mov_b32 s47, 0
	s_nop 0
	s_nop 0
	s_nop 0
	s_nop 0
	s_nop 0
	s_nop 0
	s_nop 0
	s_nop 0
	v_add_u32_e32 v105, s3, v138
	v_add_u32_e32 v102, v105, v143
	ds_read_b128 a[16:19], v102
	v_add_u32_e32 v103, v105, v144
	ds_read_b128 a[20:23], v103
	v_add_u32_e32 v104, v145, v138
	ds_read_b128 a[24:27], v104
	v_add_u32_e32 v105, v105, v132
	ds_read_b128 a[28:31], v105
	s_waitcnt lgkmcnt(4)
	v_mfma_f32_32x32x16_bf16 v[48:63], a[0:3], a[8:11], v[48:63]
	s_nop 0
	v_mfma_f32_32x32x16_bf16 v[32:47], a[4:7], a[8:11], v[32:47]
	s_nop 0
	s_nop 0
	s_nop 0
	s_nop 0
	s_nop 0
	v_mfma_f32_32x32x16_bf16 v[16:31], a[0:3], a[12:15], v[16:31]
	s_and_b32 m0, s32, 7
	s_lshl_b32 m0, m0, 12
	s_add_i32 m0, m0, 0xc400
	s_nop 0
	global_load_lds_dwordx4 v[172:173], off
	s_nop 0
	v_mfma_f32_32x32x16_bf16 v[0:15], a[4:7], a[12:15], v[0:15]
	s_nop 0
	s_nop 0
	s_nop 0
	v_add_u32_e32 v109, s3, v139
	v_add_u32_e32 v106, v109, v143
	ds_read_b128 a[0:3], v106
	v_add_u32_e32 v107, v109, v144
	ds_read_b128 a[4:7], v107
	v_add_u32_e32 v108, v145, v139
	ds_read_b128 a[8:11], v108
	v_add_u32_e32 v109, v109, v132
	ds_read_b128 a[12:15], v109
	s_waitcnt lgkmcnt(5)
	v_mfma_f32_32x32x16_bf16 v[48:63], a[16:19], a[24:27], v[48:63]
	v_mfma_f32_32x32x16_bf16 v[32:47], a[20:23], a[24:27], v[32:47]
	s_and_b32 m0, s32, 7
	s_lshl_b32 m0, m0, 12
	s_add_i32 m0, m0, 0xc800
	s_nop 0
	global_load_lds_dwordx4 v[174:175], off
	s_waitcnt lgkmcnt(4)
	v_mfma_f32_32x32x16_bf16 v[16:31], a[16:19], a[28:31], v[16:31]
	s_nop 0
	s_nop 0
	s_nop 0
	s_nop 0
	s_nop 0
	s_nop 0
	v_mfma_f32_32x32x16_bf16 v[0:15], a[20:23], a[28:31], v[0:15]
	s_nop 0
	s_nop 0
	s_nop 0
	v_add_u32_e32 v113, s3, v142
	v_add_u32_e32 v110, v113, v143
	ds_read_b128 a[16:19], v110
	v_add_u32_e32 v111, v113, v144
	ds_read_b128 a[20:23], v111
	v_add_u32_e32 v112, v145, v142
	ds_read_b128 a[24:27], v112
	v_add_u32_e32 v113, v113, v132
	ds_read_b128 a[28:31], v113
	s_waitcnt lgkmcnt(5)
	v_mfma_f32_32x32x16_bf16 v[48:63], a[0:3], a[8:11], v[48:63]
	s_and_b32 m0, s32, 7
	s_lshl_b32 m0, m0, 12
	s_add_i32 m0, m0, 0xcc00
	s_nop 0
	global_load_lds_dwordx4 v[176:177], off
	v_mfma_f32_32x32x16_bf16 v[32:47], a[4:7], a[8:11], v[32:47]
	s_waitcnt lgkmcnt(4)
	v_mfma_f32_32x32x16_bf16 v[16:31], a[0:3], a[12:15], v[16:31]
	s_nop 0
	s_nop 0
	s_nop 0
	s_nop 0
	s_nop 0
	s_nop 0
	v_mfma_f32_32x32x16_bf16 v[0:15], a[4:7], a[12:15], v[0:15]
	s_and_b32 m0, s32, 7
	s_lshl_b32 m0, m0, 11
	s_add_i32 m0, m0, 0x14000
	s_nop 0
	global_load_lds_dwordx4 v[178:179], off
	s_nop 0
	s_nop 0
	s_nop 0
	s_waitcnt lgkmcnt(1)
	v_mfma_f32_32x32x16_bf16 v[48:63], a[16:19], a[24:27], v[48:63]
	v_mfma_f32_32x32x16_bf16 v[32:47], a[20:23], a[24:27], v[32:47]
	s_and_b32 m0, s32, 7
	s_lshl_b32 m0, m0, 11
	s_add_i32 m0, m0, 0x14400
	s_nop 0
	global_load_lds_dwordx4 v[180:181], off
	s_waitcnt vmcnt(6)
	s_waitcnt lgkmcnt(0)
	s_barrier
	ds_read_b128 a[12:15], v82 offset:4096
	ds_read_b128 a[8:11], v82
	ds_read_b128 a[4:7], v83 offset:36864
	ds_read_b128 a[0:3], v83 offset:32768
	v_mfma_f32_32x32x16_bf16 v[16:31], a[16:19], a[28:31], v[16:31]
	v_lshl_add_u64 v[158:159], v[66:67], 0, s[46:47]
	s_nop 0
	v_lshl_add_u64 v[160:161], v[68:69], 0, s[46:47]
	s_nop 0
	s_nop 0
	s_nop 0
	v_lshl_add_u64 v[162:163], v[70:71], 0, s[46:47]
	s_nop 0
	v_mfma_f32_32x32x16_bf16 v[0:15], a[20:23], a[28:31], v[0:15]
	s_and_b32 m0, s32, 7
	s_lshl_b32 m0, m0, 12
	s_add_i32 m0, m0, 0x18000
	s_nop 0
	global_load_lds_dwordx4 v[158:159], off
	s_nop 0
	v_lshl_add_u64 v[164:165], v[72:73], 0, s[46:47]
	s_nop 0
	s_nop 0
	s_nop 0
	v_lshl_add_u64 v[166:167], v[74:75], 0, s[46:47]
	s_nop 0
	s_nop 0
	s_nop 0
	v_lshl_add_u64 v[168:169], v[76:77], 0, s[46:47]
	s_nop 0
	s_lshr_b32 s46, s32, 15
	s_add_i32 s46, s46, 5
	s_sub_i32 s47, s46, 15
	s_cmp_ge_u32 s46, 15
	s_cselect_b32 s46, s47, s46
	s_add_i32 s46, s46, 1
	s_lshl_b32 s46, s46, 7
	s_mov_b32 s47, 0
	s_nop 0
	s_nop 0
	s_nop 0
	s_nop 0
	s_nop 0
	ds_read_b128 a[16:19], v85 offset:32768
	ds_read_b128 a[20:23], v85 offset:36864
	ds_read_b128 a[24:27], v84
	ds_read_b128 a[28:31], v84 offset:4096
	s_waitcnt lgkmcnt(4)
	v_mfma_f32_32x32x16_bf16 v[48:63], a[0:3], a[8:11], v[48:63]
	s_nop 0
	v_mfma_f32_32x32x16_bf16 v[32:47], a[4:7], a[8:11], v[32:47]
	v_mfma_f32_32x32x16_bf16 v[16:31], a[0:3], a[12:15], v[16:31]
	s_and_b32 m0, s32, 7
	s_lshl_b32 m0, m0, 12
	s_add_i32 m0, m0, 0x18400
	s_nop 0
	global_load_lds_dwordx4 v[160:161], off
	v_mfma_f32_32x32x16_bf16 v[0:15], a[4:7], a[12:15], v[0:15]
	s_nop 0
	s_nop 0
	s_nop 0
	s_nop 0
	ds_read_b128 a[0:3], v87 offset:32768
	ds_read_b128 a[4:7], v87 offset:36864
	ds_read_b128 a[8:11], v86
	ds_read_b128 a[12:15], v86 offset:4096
	s_waitcnt lgkmcnt(5)
	v_mfma_f32_32x32x16_bf16 v[48:63], a[16:19], a[24:27], v[48:63]
	v_mfma_f32_32x32x16_bf16 v[32:47], a[20:23], a[24:27], v[32:47]
	s_and_b32 m0, s32, 7
	s_lshl_b32 m0, m0, 12
	s_add_i32 m0, m0, 0x18800
	s_nop 0
	global_load_lds_dwordx4 v[162:163], off
	s_waitcnt lgkmcnt(4)
	v_mfma_f32_32x32x16_bf16 v[16:31], a[16:19], a[28:31], v[16:31]
	v_mfma_f32_32x32x16_bf16 v[0:15], a[20:23], a[28:31], v[0:15]
	s_nop 0
	s_nop 0
	s_nop 0
	s_nop 0
	ds_read_b128 a[16:19], v89 offset:32768
	ds_read_b128 a[20:23], v89 offset:36864
	ds_read_b128 a[24:27], v88
	ds_read_b128 a[28:31], v88 offset:4096
	s_waitcnt lgkmcnt(5)
	v_mfma_f32_32x32x16_bf16 v[48:63], a[0:3], a[8:11], v[48:63]
	s_and_b32 m0, s32, 7
	s_lshl_b32 m0, m0, 12
	s_add_i32 m0, m0, 0x18c00
	s_nop 0
	global_load_lds_dwordx4 v[164:165], off
	v_mfma_f32_32x32x16_bf16 v[32:47], a[4:7], a[8:11], v[32:47]
	s_waitcnt lgkmcnt(4)
	v_mfma_f32_32x32x16_bf16 v[16:31], a[0:3], a[12:15], v[16:31]
	v_mfma_f32_32x32x16_bf16 v[0:15], a[4:7], a[12:15], v[0:15]
	s_and_b32 m0, s32, 7
	s_lshl_b32 m0, m0, 11
	s_add_i32 m0, m0, 0x20000
	s_nop 0
	global_load_lds_dwordx4 v[166:167], off
	s_nop 0
	s_nop 0
	s_nop 0
	s_nop 0
	s_waitcnt lgkmcnt(1)
	v_mfma_f32_32x32x16_bf16 v[48:63], a[16:19], a[24:27], v[48:63]
	v_mfma_f32_32x32x16_bf16 v[32:47], a[20:23], a[24:27], v[32:47]
	s_and_b32 m0, s32, 7
	s_lshl_b32 m0, m0, 11
	s_add_i32 m0, m0, 0x20400
	s_nop 0
	global_load_lds_dwordx4 v[168:169], off
	s_waitcnt vmcnt(6)
	s_waitcnt lgkmcnt(0)
	s_barrier
	ds_read_b128 a[12:15], v82 offset:53248
	ds_read_b128 a[8:11], v82 offset:49152
	ds_read_b128 a[4:7], v90
	ds_read_b128 a[0:3], v92
	v_mfma_f32_32x32x16_bf16 v[16:31], a[16:19], a[28:31], v[16:31]
	v_lshl_add_u64 v[170:171], v[66:67], 0, s[46:47]
	s_nop 0
	v_lshl_add_u64 v[172:173], v[68:69], 0, s[46:47]
	s_nop 0
	s_nop 0
	s_nop 0
	v_lshl_add_u64 v[174:175], v[70:71], 0, s[46:47]
	s_nop 0
	v_mfma_f32_32x32x16_bf16 v[0:15], a[20:23], a[28:31], v[0:15]
	s_and_b32 m0, s32, 7
	s_lshl_b32 m0, m0, 12
	s_add_i32 m0, m0, 0x0
	s_nop 0
	global_load_lds_dwordx4 v[170:171], off
	s_nop 0
	v_lshl_add_u64 v[176:177], v[72:73], 0, s[46:47]
	s_nop 0
	s_lshr_b32 s38, s32, 15
	s_add_i32 s38, s38, 6
	s_sub_i32 s39, s38, 15
	s_cmp_ge_u32 s38, 15
	s_cselect_b32 s38, s39, s38
	s_add_i32 s38, s38, 1
	s_lshl_b32 s38, s38, 7
	s_mov_b32 s39, 0
	s_nop 0
	v_lshl_add_u64 v[178:179], v[74:75], 0, s[46:47]
	s_nop 0
	v_readfirstlane_b32 s48, v117
	s_nop 0
	v_lshl_add_u64 v[180:181], v[76:77], 0, s[46:47]
	s_nop 0
	s_lshr_b32 s46, s32, 15
	s_add_i32 s46, s46, 10
	s_sub_i32 s47, s46, 15
	s_cmp_ge_u32 s46, 15
	s_cselect_b32 s46, s47, s46
	s_add_i32 s46, s46, 1
	s_lshl_b32 s46, s46, 7
	s_mov_b32 s47, 0
	s_nop 0
	s_nop 0
	s_nop 0
	s_nop 0
	s_nop 0
	ds_read_b128 a[16:19], v93
	ds_read_b128 a[20:23], v91
	ds_read_b128 a[24:27], v84 offset:49152
	ds_read_b128 a[28:31], v84 offset:53248
	s_waitcnt lgkmcnt(4)
	v_mfma_f32_32x32x16_bf16 v[48:63], a[0:3], a[8:11], v[48:63]
	s_nop 0
	v_readfirstlane_b32 s49, v118
	v_readfirstlane_b32 s53, v119
	v_mfma_f32_32x32x16_bf16 v[32:47], a[4:7], a[8:11], v[32:47]
	v_mfma_f32_32x32x16_bf16 v[16:31], a[0:3], a[12:15], v[16:31]
	s_and_b32 m0, s32, 7
	s_lshl_b32 m0, m0, 12
	s_add_i32 m0, m0, 0x400
	s_nop 0
	global_load_lds_dwordx4 v[172:173], off
	v_mfma_f32_32x32x16_bf16 v[0:15], a[4:7], a[12:15], v[0:15]
	s_nop 0
	s_nop 0
	s_nop 0
	s_nop 0
	ds_read_b128 a[0:3], v95
	ds_read_b128 a[4:7], v94
	ds_read_b128 a[8:11], v86 offset:49152
	ds_read_b128 a[12:15], v86 offset:53248
	s_waitcnt lgkmcnt(5)
	v_mfma_f32_32x32x16_bf16 v[48:63], a[16:19], a[24:27], v[48:63]
	v_mfma_f32_32x32x16_bf16 v[32:47], a[20:23], a[24:27], v[32:47]
	s_and_b32 m0, s32, 7
	s_lshl_b32 m0, m0, 12
	s_add_i32 m0, m0, 0x800
	s_nop 0
	global_load_lds_dwordx4 v[174:175], off
	s_waitcnt lgkmcnt(4)
	v_mfma_f32_32x32x16_bf16 v[16:31], a[16:19], a[28:31], v[16:31]
	v_mfma_f32_32x32x16_bf16 v[0:15], a[20:23], a[28:31], v[0:15]
	s_nop 0
	s_nop 0
	s_nop 0
	s_nop 0
	ds_read_b128 a[16:19], v97
	ds_read_b128 a[20:23], v96
	ds_read_b128 a[24:27], v88 offset:49152
	ds_read_b128 a[28:31], v88 offset:53248
	s_waitcnt lgkmcnt(5)
	v_mfma_f32_32x32x16_bf16 v[48:63], a[0:3], a[8:11], v[48:63]
	s_and_b32 m0, s32, 7
	s_lshl_b32 m0, m0, 12
	s_add_i32 m0, m0, 0xc00
	s_nop 0
	global_load_lds_dwordx4 v[176:177], off
	v_mfma_f32_32x32x16_bf16 v[32:47], a[4:7], a[8:11], v[32:47]
	s_waitcnt lgkmcnt(4)
	v_mfma_f32_32x32x16_bf16 v[16:31], a[0:3], a[12:15], v[16:31]
	v_mfma_f32_32x32x16_bf16 v[0:15], a[4:7], a[12:15], v[0:15]
	s_and_b32 m0, s32, 7
	s_lshl_b32 m0, m0, 11
	s_add_i32 m0, m0, 0x8000
	s_nop 0
	global_load_lds_dwordx4 v[178:179], off
	s_nop 0
	s_nop 0
	s_nop 0
	s_nop 0
	s_waitcnt lgkmcnt(1)
	v_mfma_f32_32x32x16_bf16 v[48:63], a[16:19], a[24:27], v[48:63]
	v_mfma_f32_32x32x16_bf16 v[32:47], a[20:23], a[24:27], v[32:47]
	s_and_b32 m0, s32, 7
	s_lshl_b32 m0, m0, 11
	s_add_i32 m0, m0, 0x8400
	s_nop 0
	global_load_lds_dwordx4 v[180:181], off
	s_waitcnt vmcnt(6)
	s_waitcnt lgkmcnt(0)
	s_barrier
	ds_read_b128 a[12:15], v101
	ds_read_b128 a[8:11], v100
	ds_read_b128 a[4:7], v99
	ds_read_b128 a[0:3], v98
	v_mfma_f32_32x32x16_bf16 v[16:31], a[16:19], a[28:31], v[16:31]
	v_lshl_add_u64 v[158:159], v[66:67], 0, s[38:39]
	s_nop 0
	v_lshl_add_u64 v[160:161], v[68:69], 0, s[38:39]
	s_nop 0
	s_lshr_b32 s28, s32, 15
	s_add_i32 s28, s28, 7
	s_sub_i32 s29, s28, 15
	s_cmp_ge_u32 s28, 15
	s_cselect_b32 s28, s29, s28
	s_add_i32 s28, s28, 1
	s_lshl_b32 s28, s28, 7
	s_mov_b32 s29, 0
	s_nop 0
	v_lshl_add_u64 v[162:163], v[70:71], 0, s[38:39]
	s_nop 0
	v_mfma_f32_32x32x16_bf16 v[0:15], a[20:23], a[28:31], v[0:15]
	s_and_b32 m0, s32, 7
	s_lshl_b32 m0, m0, 12
	s_add_i32 m0, m0, 0xc000
	s_nop 0
	global_load_lds_dwordx4 v[158:159], off
	s_nop 0
	v_lshl_add_u64 v[164:165], v[72:73], 0, s[38:39]
	s_nop 0
	v_readfirstlane_b32 s33, v122
	s_nop 0
	v_lshl_add_u64 v[166:167], v[74:75], 0, s[38:39]
	s_nop 0
	v_readfirstlane_b32 s34, v123
	s_nop 0
	v_lshl_add_u64 v[168:169], v[76:77], 0, s[38:39]
	s_nop 0
	s_lshr_b32 s36, s32, 15
	s_add_i32 s36, s36, 9
	s_sub_i32 s37, s36, 15
	s_cmp_ge_u32 s36, 15
	s_cselect_b32 s36, s37, s36
	s_add_i32 s36, s36, 1
	s_lshl_b32 s36, s36, 7
	s_mov_b32 s37, 0
	s_nop 0
	s_nop 0
	s_nop 0
	s_nop 0
	s_nop 0
	ds_read_b128 a[16:19], v102
	ds_read_b128 a[20:23], v103
	ds_read_b128 a[24:27], v104
	ds_read_b128 a[28:31], v105
	s_waitcnt lgkmcnt(4)
	v_mfma_f32_32x32x16_bf16 v[48:63], a[0:3], a[8:11], v[48:63]
	s_nop 0
	v_readfirstlane_b32 s0, v126
	v_readfirstlane_b32 s35, v124
	v_readfirstlane_b32 s38, v115
	v_readfirstlane_b32 s39, v116
	v_mfma_f32_32x32x16_bf16 v[32:47], a[4:7], a[8:11], v[32:47]
	v_mfma_f32_32x32x16_bf16 v[16:31], a[0:3], a[12:15], v[16:31]
	s_and_b32 m0, s32, 7
	s_lshl_b32 m0, m0, 12
	s_add_i32 m0, m0, 0xc400
	s_nop 0
	global_load_lds_dwordx4 v[160:161], off
	v_mfma_f32_32x32x16_bf16 v[0:15], a[4:7], a[12:15], v[0:15]
	s_nop 0
	s_nop 0
	s_nop 0
	s_nop 0
	ds_read_b128 a[0:3], v106
	ds_read_b128 a[4:7], v107
	ds_read_b128 a[8:11], v108
	ds_read_b128 a[12:15], v109
	s_waitcnt lgkmcnt(5)
	v_mfma_f32_32x32x16_bf16 v[48:63], a[16:19], a[24:27], v[48:63]
	v_mfma_f32_32x32x16_bf16 v[32:47], a[20:23], a[24:27], v[32:47]
	s_and_b32 m0, s32, 7
	s_lshl_b32 m0, m0, 12
	s_add_i32 m0, m0, 0xc800
	s_nop 0
	global_load_lds_dwordx4 v[162:163], off
	s_waitcnt lgkmcnt(4)
	v_mfma_f32_32x32x16_bf16 v[16:31], a[16:19], a[28:31], v[16:31]
	v_mfma_f32_32x32x16_bf16 v[0:15], a[20:23], a[28:31], v[0:15]
	s_nop 0
	s_nop 0
	s_nop 0
	s_nop 0
	ds_read_b128 a[16:19], v110
	ds_read_b128 a[20:23], v111
	ds_read_b128 a[24:27], v112
	ds_read_b128 a[28:31], v113
	s_waitcnt lgkmcnt(5)
	v_mfma_f32_32x32x16_bf16 v[48:63], a[0:3], a[8:11], v[48:63]
	s_and_b32 m0, s32, 7
	s_lshl_b32 m0, m0, 12
	s_add_i32 m0, m0, 0xcc00
	s_nop 0
	global_load_lds_dwordx4 v[164:165], off
	v_mfma_f32_32x32x16_bf16 v[32:47], a[4:7], a[8:11], v[32:47]
	s_waitcnt lgkmcnt(4)
	v_mfma_f32_32x32x16_bf16 v[16:31], a[0:3], a[12:15], v[16:31]
	v_mfma_f32_32x32x16_bf16 v[0:15], a[4:7], a[12:15], v[0:15]
	s_and_b32 m0, s32, 7
	s_lshl_b32 m0, m0, 11
	s_add_i32 m0, m0, 0x14000
	s_nop 0
	global_load_lds_dwordx4 v[166:167], off
	s_nop 0
	s_nop 0
	s_nop 0
	s_nop 0
	s_waitcnt lgkmcnt(1)
	v_mfma_f32_32x32x16_bf16 v[48:63], a[16:19], a[24:27], v[48:63]
	v_mfma_f32_32x32x16_bf16 v[32:47], a[20:23], a[24:27], v[32:47]
	s_and_b32 m0, s32, 7
	s_lshl_b32 m0, m0, 11
	s_add_i32 m0, m0, 0x14400
	s_nop 0
	global_load_lds_dwordx4 v[168:169], off
	s_waitcnt vmcnt(6)
	s_waitcnt lgkmcnt(0)
	s_barrier
	ds_read_b128 a[12:15], v82 offset:4096
	ds_read_b128 a[8:11], v82
	ds_read_b128 a[4:7], v83 offset:36864
	ds_read_b128 a[0:3], v83 offset:32768
	v_mfma_f32_32x32x16_bf16 v[16:31], a[16:19], a[28:31], v[16:31]
	v_lshl_add_u64 v[170:171], v[66:67], 0, s[28:29]
	s_nop 0
	v_lshl_add_u64 v[172:173], v[68:69], 0, s[28:29]
	s_nop 0
	v_readfirstlane_b32 s1, v127
	s_nop 0
	v_lshl_add_u64 v[174:175], v[70:71], 0, s[28:29]
	s_nop 0
	v_mfma_f32_32x32x16_bf16 v[0:15], a[20:23], a[28:31], v[0:15]
	s_and_b32 m0, s32, 7
	s_lshl_b32 m0, m0, 12
	s_add_i32 m0, m0, 0x18000
	s_nop 0
	global_load_lds_dwordx4 v[170:171], off
	s_nop 0
	v_lshl_add_u64 v[176:177], v[72:73], 0, s[28:29]
	s_nop 0
	v_readfirstlane_b32 s20, v128
	s_nop 0
	v_lshl_add_u64 v[178:179], v[74:75], 0, s[28:29]
	s_nop 0
	v_readfirstlane_b32 s21, v129
	s_nop 0
	v_lshl_add_u64 v[180:181], v[76:77], 0, s[28:29]
	s_nop 0
	s_lshr_b32 s28, s32, 15
	s_add_i32 s28, s28, 8
	s_sub_i32 s29, s28, 15
	s_cmp_ge_u32 s28, 15
	s_cselect_b32 s28, s29, s28
	s_add_i32 s28, s28, 1
	s_lshl_b32 s28, s28, 7
	s_mov_b32 s29, 0
	s_nop 0
	s_nop 0
	s_nop 0
	s_nop 0
	s_nop 0
	ds_read_b128 a[16:19], v85 offset:32768
	ds_read_b128 a[20:23], v85 offset:36864
	ds_read_b128 a[24:27], v84
	ds_read_b128 a[28:31], v84 offset:4096
	s_waitcnt lgkmcnt(4)
	v_mfma_f32_32x32x16_bf16 v[48:63], a[0:3], a[8:11], v[48:63]
	s_nop 0
	v_lshl_add_u64 v[162:163], v[70:71], 0, s[28:29]
	v_readfirstlane_b32 s23, v131
	v_readfirstlane_b32 s24, v130
	v_mfma_f32_32x32x16_bf16 v[32:47], a[4:7], a[8:11], v[32:47]
	v_mfma_f32_32x32x16_bf16 v[16:31], a[0:3], a[12:15], v[16:31]
	s_and_b32 m0, s32, 7
	s_lshl_b32 m0, m0, 12
	s_add_i32 m0, m0, 0x18400
	s_nop 0
	global_load_lds_dwordx4 v[172:173], off
	v_mfma_f32_32x32x16_bf16 v[0:15], a[4:7], a[12:15], v[0:15]
	s_nop 0
	s_nop 0
	s_nop 0
	s_nop 0
	ds_read_b128 a[0:3], v87 offset:32768
	ds_read_b128 a[4:7], v87 offset:36864
	ds_read_b128 a[8:11], v86
	ds_read_b128 a[12:15], v86 offset:4096
	s_waitcnt lgkmcnt(5)
	v_mfma_f32_32x32x16_bf16 v[48:63], a[16:19], a[24:27], v[48:63]
	v_mfma_f32_32x32x16_bf16 v[32:47], a[20:23], a[24:27], v[32:47]
	s_and_b32 m0, s32, 7
	s_lshl_b32 m0, m0, 12
	s_add_i32 m0, m0, 0x18800
	s_nop 0
	global_load_lds_dwordx4 v[174:175], off
	s_waitcnt lgkmcnt(4)
	v_mfma_f32_32x32x16_bf16 v[16:31], a[16:19], a[28:31], v[16:31]
	v_mfma_f32_32x32x16_bf16 v[0:15], a[20:23], a[28:31], v[0:15]
	s_nop 0
	s_nop 0
	s_nop 0
	s_nop 0
	ds_read_b128 a[16:19], v89 offset:32768
	ds_read_b128 a[20:23], v89 offset:36864
	ds_read_b128 a[24:27], v88
	ds_read_b128 a[28:31], v88 offset:4096
	s_waitcnt lgkmcnt(5)
	v_mfma_f32_32x32x16_bf16 v[48:63], a[0:3], a[8:11], v[48:63]
	s_and_b32 m0, s32, 7
	s_lshl_b32 m0, m0, 12
	s_add_i32 m0, m0, 0x18c00
	s_nop 0
	global_load_lds_dwordx4 v[176:177], off
	v_mfma_f32_32x32x16_bf16 v[32:47], a[4:7], a[8:11], v[32:47]
	s_waitcnt lgkmcnt(4)
	v_mfma_f32_32x32x16_bf16 v[16:31], a[0:3], a[12:15], v[16:31]
	v_mfma_f32_32x32x16_bf16 v[0:15], a[4:7], a[12:15], v[0:15]
	s_and_b32 m0, s32, 7
	s_lshl_b32 m0, m0, 11
	s_add_i32 m0, m0, 0x20000
	s_nop 0
	global_load_lds_dwordx4 v[178:179], off
	s_nop 0
	s_nop 0
	s_nop 0
	s_nop 0
	s_waitcnt lgkmcnt(1)
	v_mfma_f32_32x32x16_bf16 v[48:63], a[16:19], a[24:27], v[48:63]
	v_mfma_f32_32x32x16_bf16 v[32:47], a[20:23], a[24:27], v[32:47]
	s_and_b32 m0, s32, 7
	s_lshl_b32 m0, m0, 11
	s_add_i32 m0, m0, 0x20400
	s_nop 0
	global_load_lds_dwordx4 v[180:181], off
	s_waitcnt vmcnt(6)
	s_waitcnt lgkmcnt(0)
	s_barrier
	ds_read_b128 a[12:15], v82 offset:53248
	ds_read_b128 a[8:11], v82 offset:49152
	ds_read_b128 a[4:7], v90
	ds_read_b128 a[0:3], v92
	v_mfma_f32_32x32x16_bf16 v[16:31], a[16:19], a[28:31], v[16:31]
	v_lshl_add_u64 v[158:159], v[66:67], 0, s[28:29]
	s_nop 0
	v_lshl_add_u64 v[160:161], v[68:69], 0, s[28:29]
	s_nop 0
	s_nop 0
	s_nop 0
	s_nop 0
	v_mfma_f32_32x32x16_bf16 v[0:15], a[20:23], a[28:31], v[0:15]
	s_and_b32 m0, s32, 7
	s_lshl_b32 m0, m0, 12
	s_add_i32 m0, m0, 0x0
	s_nop 0
	global_load_lds_dwordx4 v[158:159], off
	s_nop 0
	v_lshl_add_u64 v[164:165], v[72:73], 0, s[28:29]
	s_nop 0
	s_nop 0
	s_nop 0
	v_lshl_add_u64 v[166:167], v[74:75], 0, s[28:29]
	s_nop 0
	s_nop 0
	s_nop 0
	v_lshl_add_u64 v[168:169], v[76:77], 0, s[28:29]
	s_nop 0
	v_readfirstlane_b32 s28, v120
	s_nop 0
	s_nop 0
	s_nop 0
	s_nop 0
	s_nop 0
	ds_read_b128 a[16:19], v93
	ds_read_b128 a[20:23], v91
	ds_read_b128 a[24:27], v84 offset:49152
	ds_read_b128 a[28:31], v84 offset:53248
	s_waitcnt lgkmcnt(4)
	v_mfma_f32_32x32x16_bf16 v[48:63], a[0:3], a[8:11], v[48:63]
	s_nop 0
	v_readfirstlane_b32 s29, v121
	v_lshl_add_u64 v[174:175], v[70:71], 0, s[36:37]
	v_mfma_f32_32x32x16_bf16 v[32:47], a[4:7], a[8:11], v[32:47]
	v_mfma_f32_32x32x16_bf16 v[16:31], a[0:3], a[12:15], v[16:31]
	s_and_b32 m0, s32, 7
	s_lshl_b32 m0, m0, 12
	s_add_i32 m0, m0, 0x400
	s_nop 0
	global_load_lds_dwordx4 v[160:161], off
	v_mfma_f32_32x32x16_bf16 v[0:15], a[4:7], a[12:15], v[0:15]
	s_nop 0
	s_nop 0
	s_nop 0
	s_nop 0
	ds_read_b128 a[0:3], v95
	ds_read_b128 a[4:7], v94
	ds_read_b128 a[8:11], v86 offset:49152
	ds_read_b128 a[12:15], v86 offset:53248
	s_waitcnt lgkmcnt(5)
	v_mfma_f32_32x32x16_bf16 v[48:63], a[16:19], a[24:27], v[48:63]
	v_mfma_f32_32x32x16_bf16 v[32:47], a[20:23], a[24:27], v[32:47]
	s_and_b32 m0, s32, 7
	s_lshl_b32 m0, m0, 12
	s_add_i32 m0, m0, 0x800
	s_nop 0
	global_load_lds_dwordx4 v[162:163], off
	s_waitcnt lgkmcnt(4)
	v_mfma_f32_32x32x16_bf16 v[16:31], a[16:19], a[28:31], v[16:31]
	v_mfma_f32_32x32x16_bf16 v[0:15], a[20:23], a[28:31], v[0:15]
	s_nop 0
	s_nop 0
	s_nop 0
	s_nop 0
	ds_read_b128 a[16:19], v97
	ds_read_b128 a[20:23], v96
	ds_read_b128 a[24:27], v88 offset:49152
	ds_read_b128 a[28:31], v88 offset:53248
	s_waitcnt lgkmcnt(5)
	v_mfma_f32_32x32x16_bf16 v[48:63], a[0:3], a[8:11], v[48:63]
	s_and_b32 m0, s32, 7
	s_lshl_b32 m0, m0, 12
	s_add_i32 m0, m0, 0xc00
	s_nop 0
	global_load_lds_dwordx4 v[164:165], off
	v_mfma_f32_32x32x16_bf16 v[32:47], a[4:7], a[8:11], v[32:47]
	s_waitcnt lgkmcnt(4)
	v_mfma_f32_32x32x16_bf16 v[16:31], a[0:3], a[12:15], v[16:31]
	v_mfma_f32_32x32x16_bf16 v[0:15], a[4:7], a[12:15], v[0:15]
	s_and_b32 m0, s32, 7
	s_lshl_b32 m0, m0, 11
	s_add_i32 m0, m0, 0x8000
	s_nop 0
	global_load_lds_dwordx4 v[166:167], off
	s_nop 0
	s_nop 0
	s_nop 0
	s_nop 0
	s_waitcnt lgkmcnt(1)
	v_mfma_f32_32x32x16_bf16 v[48:63], a[16:19], a[24:27], v[48:63]
	v_mfma_f32_32x32x16_bf16 v[32:47], a[20:23], a[24:27], v[32:47]
	s_and_b32 m0, s32, 7
	s_lshl_b32 m0, m0, 11
	s_add_i32 m0, m0, 0x8400
	s_nop 0
	global_load_lds_dwordx4 v[168:169], off
	s_waitcnt vmcnt(6)
	s_waitcnt lgkmcnt(0)
	s_barrier
	ds_read_b128 a[12:15], v101
	ds_read_b128 a[8:11], v100
	ds_read_b128 a[4:7], v99
	ds_read_b128 a[0:3], v98
	v_mfma_f32_32x32x16_bf16 v[16:31], a[16:19], a[28:31], v[16:31]
	v_lshl_add_u64 v[170:171], v[66:67], 0, s[36:37]
	s_nop 0
	v_lshl_add_u64 v[172:173], v[68:69], 0, s[36:37]
	s_nop 0
	s_nop 0
	s_nop 0
	s_nop 0
	v_mfma_f32_32x32x16_bf16 v[0:15], a[20:23], a[28:31], v[0:15]
	s_and_b32 m0, s32, 7
	s_lshl_b32 m0, m0, 12
	s_add_i32 m0, m0, 0xc000
	s_nop 0
	global_load_lds_dwordx4 v[170:171], off
	s_nop 0
	v_lshl_add_u64 v[176:177], v[72:73], 0, s[36:37]
	s_nop 0
	s_nop 0
	s_nop 0
	v_lshl_add_u64 v[178:179], v[74:75], 0, s[36:37]
	s_nop 0
	s_nop 0
	s_nop 0
	v_lshl_add_u64 v[180:181], v[76:77], 0, s[36:37]
	v_readfirstlane_b32 s36, v125
	s_nop 0
	v_readfirstlane_b32 s37, v114
	s_nop 0
	s_nop 0
	s_nop 0
	s_nop 0
	s_nop 0
	ds_read_b128 a[16:19], v102
	ds_read_b128 a[20:23], v103
	ds_read_b128 a[24:27], v104
	ds_read_b128 a[28:31], v105
	s_waitcnt lgkmcnt(4)
	v_mfma_f32_32x32x16_bf16 v[48:63], a[0:3], a[8:11], v[48:63]
	s_nop 0
	v_lshl_add_u64 v[162:163], v[70:71], 0, s[46:47]
	v_mfma_f32_32x32x16_bf16 v[32:47], a[4:7], a[8:11], v[32:47]
	v_mfma_f32_32x32x16_bf16 v[16:31], a[0:3], a[12:15], v[16:31]
	s_and_b32 m0, s32, 7
	s_lshl_b32 m0, m0, 12
	s_add_i32 m0, m0, 0xc400
	s_nop 0
	global_load_lds_dwordx4 v[172:173], off
	v_mfma_f32_32x32x16_bf16 v[0:15], a[4:7], a[12:15], v[0:15]
	s_nop 0
	s_nop 0
	s_nop 0
	s_nop 0
	ds_read_b128 a[0:3], v106
	ds_read_b128 a[4:7], v107
	ds_read_b128 a[8:11], v108
	ds_read_b128 a[12:15], v109
	s_waitcnt lgkmcnt(5)
	v_mfma_f32_32x32x16_bf16 v[48:63], a[16:19], a[24:27], v[48:63]
	v_mfma_f32_32x32x16_bf16 v[32:47], a[20:23], a[24:27], v[32:47]
	s_and_b32 m0, s32, 7
	s_lshl_b32 m0, m0, 12
	s_add_i32 m0, m0, 0xc800
	s_nop 0
	global_load_lds_dwordx4 v[174:175], off
	s_waitcnt lgkmcnt(4)
	v_mfma_f32_32x32x16_bf16 v[16:31], a[16:19], a[28:31], v[16:31]
	v_mfma_f32_32x32x16_bf16 v[0:15], a[20:23], a[28:31], v[0:15]
	s_nop 0
	s_nop 0
	s_nop 0
	s_nop 0
	ds_read_b128 a[16:19], v110
	ds_read_b128 a[20:23], v111
	ds_read_b128 a[24:27], v112
	ds_read_b128 a[28:31], v113
	s_waitcnt lgkmcnt(5)
	v_mfma_f32_32x32x16_bf16 v[48:63], a[0:3], a[8:11], v[48:63]
	s_and_b32 m0, s32, 7
	s_lshl_b32 m0, m0, 12
	s_add_i32 m0, m0, 0xcc00
	s_nop 0
	global_load_lds_dwordx4 v[176:177], off
	v_mfma_f32_32x32x16_bf16 v[32:47], a[4:7], a[8:11], v[32:47]
	s_waitcnt lgkmcnt(4)
	v_mfma_f32_32x32x16_bf16 v[16:31], a[0:3], a[12:15], v[16:31]
	v_mfma_f32_32x32x16_bf16 v[0:15], a[4:7], a[12:15], v[0:15]
	s_and_b32 m0, s32, 7
	s_lshl_b32 m0, m0, 11
	s_add_i32 m0, m0, 0x14000
	s_nop 0
	global_load_lds_dwordx4 v[178:179], off
	s_nop 0
	s_nop 0
	s_nop 0
	s_nop 0
	s_waitcnt lgkmcnt(1)
	v_mfma_f32_32x32x16_bf16 v[48:63], a[16:19], a[24:27], v[48:63]
	v_mfma_f32_32x32x16_bf16 v[32:47], a[20:23], a[24:27], v[32:47]
	s_and_b32 m0, s32, 7
	s_lshl_b32 m0, m0, 11
	s_add_i32 m0, m0, 0x14400
	s_nop 0
	global_load_lds_dwordx4 v[180:181], off
	s_waitcnt vmcnt(6)
	s_waitcnt lgkmcnt(0)
	s_barrier
	ds_read_b128 a[12:15], v82 offset:4096
	ds_read_b128 a[8:11], v82
	ds_read_b128 a[4:7], v83 offset:36864
	ds_read_b128 a[0:3], v83 offset:32768
	v_mfma_f32_32x32x16_bf16 v[16:31], a[16:19], a[28:31], v[16:31]
	v_lshl_add_u64 v[158:159], v[66:67], 0, s[46:47]
	s_nop 0
	v_lshl_add_u64 v[160:161], v[68:69], 0, s[46:47]
	s_nop 0
	s_nop 0
	s_nop 0
	s_nop 0
	v_mfma_f32_32x32x16_bf16 v[0:15], a[20:23], a[28:31], v[0:15]
	s_and_b32 m0, s32, 7
	s_lshl_b32 m0, m0, 12
	s_add_i32 m0, m0, 0x18000
	s_nop 0
	global_load_lds_dwordx4 v[158:159], off
	s_nop 0
	v_lshl_add_u64 v[164:165], v[72:73], 0, s[46:47]
	s_nop 0
	s_nop 0
	s_nop 0
	v_lshl_add_u64 v[166:167], v[74:75], 0, s[46:47]
	s_nop 0
	s_nop 0
	s_nop 0
	v_lshl_add_u64 v[168:169], v[76:77], 0, s[46:47]
	s_nop 0
	s_lshr_b32 s46, s32, 15
	s_add_i32 s46, s46, 11
	s_sub_i32 s47, s46, 15
	s_cmp_ge_u32 s46, 15
	s_cselect_b32 s46, s47, s46
	s_add_i32 s46, s46, 1
	s_lshl_b32 s46, s46, 7
	s_mov_b32 s47, 0
	s_nop 0
	s_nop 0
	s_nop 0
	s_nop 0
	s_nop 0
	ds_read_b128 a[16:19], v85 offset:32768
	ds_read_b128 a[20:23], v85 offset:36864
	ds_read_b128 a[24:27], v84
	ds_read_b128 a[28:31], v84 offset:4096
	s_waitcnt lgkmcnt(4)
	v_mfma_f32_32x32x16_bf16 v[48:63], a[0:3], a[8:11], v[48:63]
	s_nop 0
	v_mfma_f32_32x32x16_bf16 v[32:47], a[4:7], a[8:11], v[32:47]
	v_mfma_f32_32x32x16_bf16 v[16:31], a[0:3], a[12:15], v[16:31]
	s_and_b32 m0, s32, 7
	s_lshl_b32 m0, m0, 12
	s_add_i32 m0, m0, 0x18400
	s_nop 0
	global_load_lds_dwordx4 v[160:161], off
	v_mfma_f32_32x32x16_bf16 v[0:15], a[4:7], a[12:15], v[0:15]
	s_nop 0
	s_nop 0
	s_nop 0
	s_nop 0
	ds_read_b128 a[0:3], v87 offset:32768
	ds_read_b128 a[4:7], v87 offset:36864
	ds_read_b128 a[8:11], v86
	ds_read_b128 a[12:15], v86 offset:4096
	s_waitcnt lgkmcnt(5)
	v_mfma_f32_32x32x16_bf16 v[48:63], a[16:19], a[24:27], v[48:63]
	v_mfma_f32_32x32x16_bf16 v[32:47], a[20:23], a[24:27], v[32:47]
	s_and_b32 m0, s32, 7
	s_lshl_b32 m0, m0, 12
	s_add_i32 m0, m0, 0x18800
	s_nop 0
	global_load_lds_dwordx4 v[162:163], off
	s_waitcnt lgkmcnt(4)
	v_mfma_f32_32x32x16_bf16 v[16:31], a[16:19], a[28:31], v[16:31]
	v_mfma_f32_32x32x16_bf16 v[0:15], a[20:23], a[28:31], v[0:15]
	s_nop 0
	s_nop 0
	s_nop 0
	s_nop 0
	ds_read_b128 a[16:19], v89 offset:32768
	ds_read_b128 a[20:23], v89 offset:36864
	ds_read_b128 a[24:27], v88
	ds_read_b128 a[28:31], v88 offset:4096
	s_waitcnt lgkmcnt(5)
	v_mfma_f32_32x32x16_bf16 v[48:63], a[0:3], a[8:11], v[48:63]
	s_and_b32 m0, s32, 7
	s_lshl_b32 m0, m0, 12
	s_add_i32 m0, m0, 0x18c00
	s_nop 0
	global_load_lds_dwordx4 v[164:165], off
	v_mfma_f32_32x32x16_bf16 v[32:47], a[4:7], a[8:11], v[32:47]
	s_waitcnt lgkmcnt(4)
	v_mfma_f32_32x32x16_bf16 v[16:31], a[0:3], a[12:15], v[16:31]
	v_mfma_f32_32x32x16_bf16 v[0:15], a[4:7], a[12:15], v[0:15]
	s_and_b32 m0, s32, 7
	s_lshl_b32 m0, m0, 11
	s_add_i32 m0, m0, 0x20000
	s_nop 0
	global_load_lds_dwordx4 v[166:167], off
	s_nop 0
	s_nop 0
	s_nop 0
	s_nop 0
	s_waitcnt lgkmcnt(1)
	v_mfma_f32_32x32x16_bf16 v[48:63], a[16:19], a[24:27], v[48:63]
	v_mfma_f32_32x32x16_bf16 v[32:47], a[20:23], a[24:27], v[32:47]
	s_and_b32 m0, s32, 7
	s_lshl_b32 m0, m0, 11
	s_add_i32 m0, m0, 0x20400
	s_nop 0
	global_load_lds_dwordx4 v[168:169], off
	s_waitcnt vmcnt(6)
	s_waitcnt lgkmcnt(0)
	s_barrier
	ds_read_b128 a[12:15], v82 offset:53248
	ds_read_b128 a[8:11], v82 offset:49152
	ds_read_b128 a[4:7], v90
	ds_read_b128 a[0:3], v92
	v_mfma_f32_32x32x16_bf16 v[16:31], a[16:19], a[28:31], v[16:31]
	v_lshl_add_u64 v[170:171], v[66:67], 0, s[46:47]
	s_nop 0
	v_lshl_add_u64 v[172:173], v[68:69], 0, s[46:47]
	s_nop 0
	s_nop 0
	s_nop 0
	v_lshl_add_u64 v[174:175], v[70:71], 0, s[46:47]
	s_nop 0
	v_mfma_f32_32x32x16_bf16 v[0:15], a[20:23], a[28:31], v[0:15]
	s_and_b32 m0, s32, 7
	s_lshl_b32 m0, m0, 12
	s_add_i32 m0, m0, 0x0
	s_nop 0
	global_load_lds_dwordx4 v[170:171], off
	s_nop 0
	v_lshl_add_u64 v[176:177], v[72:73], 0, s[46:47]
	s_nop 0
	s_nop 0
	s_nop 0
	v_lshl_add_u64 v[178:179], v[74:75], 0, s[46:47]
	s_nop 0
	s_nop 0
	s_nop 0
	v_lshl_add_u64 v[180:181], v[76:77], 0, s[46:47]
	s_nop 0
	s_lshr_b32 s46, s32, 15
	s_add_i32 s46, s46, 12
	s_sub_i32 s47, s46, 15
	s_cmp_ge_u32 s46, 15
	s_cselect_b32 s46, s47, s46
	s_add_i32 s46, s46, 1
	s_lshl_b32 s46, s46, 7
	s_mov_b32 s47, 0
	s_nop 0
	s_nop 0
	s_nop 0
	s_nop 0
	s_nop 0
	ds_read_b128 a[16:19], v93
	ds_read_b128 a[20:23], v91
	ds_read_b128 a[24:27], v84 offset:49152
	ds_read_b128 a[28:31], v84 offset:53248
	s_waitcnt lgkmcnt(4)
	v_mfma_f32_32x32x16_bf16 v[48:63], a[0:3], a[8:11], v[48:63]
	s_nop 0
	v_mfma_f32_32x32x16_bf16 v[32:47], a[4:7], a[8:11], v[32:47]
	v_mfma_f32_32x32x16_bf16 v[16:31], a[0:3], a[12:15], v[16:31]
	s_and_b32 m0, s32, 7
	s_lshl_b32 m0, m0, 12
	s_add_i32 m0, m0, 0x400
	s_nop 0
	global_load_lds_dwordx4 v[172:173], off
	v_mfma_f32_32x32x16_bf16 v[0:15], a[4:7], a[12:15], v[0:15]
	s_nop 0
	s_nop 0
	s_nop 0
	s_nop 0
	ds_read_b128 a[0:3], v95
	ds_read_b128 a[4:7], v94
	ds_read_b128 a[8:11], v86 offset:49152
	ds_read_b128 a[12:15], v86 offset:53248
	s_waitcnt lgkmcnt(5)
	v_mfma_f32_32x32x16_bf16 v[48:63], a[16:19], a[24:27], v[48:63]
	v_mfma_f32_32x32x16_bf16 v[32:47], a[20:23], a[24:27], v[32:47]
	s_and_b32 m0, s32, 7
	s_lshl_b32 m0, m0, 12
	s_add_i32 m0, m0, 0x800
	s_nop 0
	global_load_lds_dwordx4 v[174:175], off
	s_waitcnt lgkmcnt(4)
	v_mfma_f32_32x32x16_bf16 v[16:31], a[16:19], a[28:31], v[16:31]
	v_mfma_f32_32x32x16_bf16 v[0:15], a[20:23], a[28:31], v[0:15]
	s_nop 0
	s_nop 0
	s_nop 0
	s_nop 0
	ds_read_b128 a[16:19], v97
	ds_read_b128 a[20:23], v96
	ds_read_b128 a[24:27], v88 offset:49152
	ds_read_b128 a[28:31], v88 offset:53248
	s_waitcnt lgkmcnt(5)
	v_mfma_f32_32x32x16_bf16 v[48:63], a[0:3], a[8:11], v[48:63]
	s_and_b32 m0, s32, 7
	s_lshl_b32 m0, m0, 12
	s_add_i32 m0, m0, 0xc00
	s_nop 0
	global_load_lds_dwordx4 v[176:177], off
	v_mfma_f32_32x32x16_bf16 v[32:47], a[4:7], a[8:11], v[32:47]
	s_waitcnt lgkmcnt(4)
	v_mfma_f32_32x32x16_bf16 v[16:31], a[0:3], a[12:15], v[16:31]
	v_mfma_f32_32x32x16_bf16 v[0:15], a[4:7], a[12:15], v[0:15]
	s_and_b32 m0, s32, 7
	s_lshl_b32 m0, m0, 11
	s_add_i32 m0, m0, 0x8000
	s_nop 0
	global_load_lds_dwordx4 v[178:179], off
	s_nop 0
	s_nop 0
	s_nop 0
	s_nop 0
	s_waitcnt lgkmcnt(1)
	v_mfma_f32_32x32x16_bf16 v[48:63], a[16:19], a[24:27], v[48:63]
	v_mfma_f32_32x32x16_bf16 v[32:47], a[20:23], a[24:27], v[32:47]
	s_and_b32 m0, s32, 7
	s_lshl_b32 m0, m0, 11
	s_add_i32 m0, m0, 0x8400
	s_nop 0
	global_load_lds_dwordx4 v[180:181], off
	s_waitcnt vmcnt(6)
	s_waitcnt lgkmcnt(0)
	s_barrier
	ds_read_b128 a[12:15], v101
	ds_read_b128 a[8:11], v100
	ds_read_b128 a[4:7], v99
	ds_read_b128 a[0:3], v98
	v_mfma_f32_32x32x16_bf16 v[16:31], a[16:19], a[28:31], v[16:31]
	v_lshl_add_u64 v[158:159], v[66:67], 0, s[46:47]
	s_nop 0
	v_lshl_add_u64 v[160:161], v[68:69], 0, s[46:47]
	s_nop 0
	s_lshr_b32 s28, s32, 15
	s_add_i32 s28, s28, 13
	s_sub_i32 s29, s28, 15
	s_cmp_ge_u32 s28, 15
	s_cselect_b32 s28, s29, s28
	s_add_i32 s28, s28, 1
	s_lshl_b32 s28, s28, 7
	s_mov_b32 s29, 0
	s_nop 0
	v_lshl_add_u64 v[162:163], v[70:71], 0, s[46:47]
	s_nop 0
	v_mfma_f32_32x32x16_bf16 v[0:15], a[20:23], a[28:31], v[0:15]
	s_and_b32 m0, s32, 7
	s_lshl_b32 m0, m0, 12
	s_add_i32 m0, m0, 0xc000
	s_nop 0
	global_load_lds_dwordx4 v[158:159], off
	s_nop 0
	v_lshl_add_u64 v[164:165], v[72:73], 0, s[46:47]
	s_nop 0
	s_nop 0
	s_nop 0
	v_lshl_add_u64 v[166:167], v[74:75], 0, s[46:47]
	s_nop 0
	s_nop 0
	s_nop 0
	v_lshl_add_u64 v[168:169], v[76:77], 0, s[46:47]
	s_nop 0
	s_nop 0
	s_nop 0
	s_nop 0
	s_nop 0
	s_nop 0
	s_nop 0
	ds_read_b128 a[16:19], v102
	ds_read_b128 a[20:23], v103
	ds_read_b128 a[24:27], v104
	ds_read_b128 a[28:31], v105
	s_waitcnt lgkmcnt(4)
	v_mfma_f32_32x32x16_bf16 v[48:63], a[0:3], a[8:11], v[48:63]
	s_nop 0
	v_mfma_f32_32x32x16_bf16 v[32:47], a[4:7], a[8:11], v[32:47]
	v_mfma_f32_32x32x16_bf16 v[16:31], a[0:3], a[12:15], v[16:31]
	s_and_b32 m0, s32, 7
	s_lshl_b32 m0, m0, 12
	s_add_i32 m0, m0, 0xc400
	s_nop 0
	global_load_lds_dwordx4 v[160:161], off
	v_mfma_f32_32x32x16_bf16 v[0:15], a[4:7], a[12:15], v[0:15]
	s_nop 0
	s_nop 0
	s_nop 0
	s_nop 0
	ds_read_b128 a[0:3], v106
	ds_read_b128 a[4:7], v107
	ds_read_b128 a[8:11], v108
	ds_read_b128 a[12:15], v109
	s_waitcnt lgkmcnt(5)
	v_mfma_f32_32x32x16_bf16 v[48:63], a[16:19], a[24:27], v[48:63]
	v_mfma_f32_32x32x16_bf16 v[32:47], a[20:23], a[24:27], v[32:47]
	s_and_b32 m0, s32, 7
	s_lshl_b32 m0, m0, 12
	s_add_i32 m0, m0, 0xc800
	s_nop 0
	global_load_lds_dwordx4 v[162:163], off
	s_waitcnt lgkmcnt(4)
	v_mfma_f32_32x32x16_bf16 v[16:31], a[16:19], a[28:31], v[16:31]
	v_mfma_f32_32x32x16_bf16 v[0:15], a[20:23], a[28:31], v[0:15]
	s_nop 0
	s_nop 0
	s_nop 0
	s_nop 0
	ds_read_b128 a[16:19], v110
	ds_read_b128 a[20:23], v111
	ds_read_b128 a[24:27], v112
	ds_read_b128 a[28:31], v113
	s_waitcnt lgkmcnt(5)
	v_mfma_f32_32x32x16_bf16 v[48:63], a[0:3], a[8:11], v[48:63]
	s_and_b32 m0, s32, 7
	s_lshl_b32 m0, m0, 12
	s_add_i32 m0, m0, 0xcc00
	s_nop 0
	global_load_lds_dwordx4 v[164:165], off
	v_mfma_f32_32x32x16_bf16 v[32:47], a[4:7], a[8:11], v[32:47]
	s_waitcnt lgkmcnt(4)
	v_mfma_f32_32x32x16_bf16 v[16:31], a[0:3], a[12:15], v[16:31]
	v_mfma_f32_32x32x16_bf16 v[0:15], a[4:7], a[12:15], v[0:15]
	s_and_b32 m0, s32, 7
	s_lshl_b32 m0, m0, 11
	s_add_i32 m0, m0, 0x14000
	s_nop 0
	global_load_lds_dwordx4 v[166:167], off
	s_nop 0
	s_nop 0
	s_nop 0
	s_nop 0
	s_waitcnt lgkmcnt(1)
	v_mfma_f32_32x32x16_bf16 v[48:63], a[16:19], a[24:27], v[48:63]
	v_mfma_f32_32x32x16_bf16 v[32:47], a[20:23], a[24:27], v[32:47]
	s_and_b32 m0, s32, 7
	s_lshl_b32 m0, m0, 11
	s_add_i32 m0, m0, 0x14400
	s_nop 0
	global_load_lds_dwordx4 v[168:169], off
	s_waitcnt vmcnt(6)
	s_waitcnt lgkmcnt(0)
	s_barrier
	ds_read_b128 a[12:15], v82 offset:4096
	ds_read_b128 a[8:11], v82
	ds_read_b128 a[4:7], v83 offset:36864
	ds_read_b128 a[0:3], v83 offset:32768
	v_mfma_f32_32x32x16_bf16 v[16:31], a[16:19], a[28:31], v[16:31]
	v_lshl_add_u64 v[170:171], v[66:67], 0, s[28:29]
	s_nop 0
	v_lshl_add_u64 v[172:173], v[68:69], 0, s[28:29]
	s_nop 0
	s_nop 0
	s_nop 0
	v_lshl_add_u64 v[174:175], v[70:71], 0, s[28:29]
	s_nop 0
	v_mfma_f32_32x32x16_bf16 v[0:15], a[20:23], a[28:31], v[0:15]
	s_and_b32 m0, s32, 7
	s_lshl_b32 m0, m0, 12
	s_add_i32 m0, m0, 0x18000
	s_nop 0
	global_load_lds_dwordx4 v[170:171], off
	s_nop 0
	v_lshl_add_u64 v[176:177], v[72:73], 0, s[28:29]
	s_nop 0
	s_nop 0
	s_nop 0
	v_lshl_add_u64 v[178:179], v[74:75], 0, s[28:29]
	s_nop 0
	s_nop 0
	s_nop 0
	v_lshl_add_u64 v[180:181], v[76:77], 0, s[28:29]
	s_nop 0
	s_lshr_b32 s28, s32, 15
	s_add_i32 s28, s28, 14
	s_sub_i32 s29, s28, 15
	s_cmp_ge_u32 s28, 15
	s_cselect_b32 s28, s29, s28
	s_add_i32 s28, s28, 1
	s_lshl_b32 s28, s28, 7
	s_mov_b32 s29, 0
	s_nop 0
	s_nop 0
	s_nop 0
	s_nop 0
	s_nop 0
	ds_read_b128 a[16:19], v85 offset:32768
	ds_read_b128 a[20:23], v85 offset:36864
	ds_read_b128 a[24:27], v84
	ds_read_b128 a[28:31], v84 offset:4096
	s_waitcnt lgkmcnt(4)
	v_mfma_f32_32x32x16_bf16 v[48:63], a[0:3], a[8:11], v[48:63]
	v_lshl_add_u64 v[158:159], v[66:67], 0, s[28:29]
	s_nop 0
	v_mfma_f32_32x32x16_bf16 v[32:47], a[4:7], a[8:11], v[32:47]
	v_mfma_f32_32x32x16_bf16 v[16:31], a[0:3], a[12:15], v[16:31]
	s_and_b32 m0, s32, 7
	s_lshl_b32 m0, m0, 12
	s_add_i32 m0, m0, 0x18400
	s_nop 0
	global_load_lds_dwordx4 v[172:173], off
	v_mfma_f32_32x32x16_bf16 v[0:15], a[4:7], a[12:15], v[0:15]
	s_nop 0
	s_nop 0
	s_nop 0
	s_nop 0
	ds_read_b128 a[0:3], v87 offset:32768
	ds_read_b128 a[4:7], v87 offset:36864
	ds_read_b128 a[8:11], v86
	ds_read_b128 a[12:15], v86 offset:4096
	s_waitcnt lgkmcnt(5)
	v_mfma_f32_32x32x16_bf16 v[48:63], a[16:19], a[24:27], v[48:63]
	v_mfma_f32_32x32x16_bf16 v[32:47], a[20:23], a[24:27], v[32:47]
	s_and_b32 m0, s32, 7
	s_lshl_b32 m0, m0, 12
	s_add_i32 m0, m0, 0x18800
	s_nop 0
	global_load_lds_dwordx4 v[174:175], off
	s_waitcnt lgkmcnt(4)
	v_mfma_f32_32x32x16_bf16 v[16:31], a[16:19], a[28:31], v[16:31]
	v_mfma_f32_32x32x16_bf16 v[0:15], a[20:23], a[28:31], v[0:15]
	s_nop 0
	s_nop 0
	s_nop 0
	s_nop 0
	ds_read_b128 a[16:19], v89 offset:32768
	ds_read_b128 a[20:23], v89 offset:36864
	ds_read_b128 a[24:27], v88
	ds_read_b128 a[28:31], v88 offset:4096
	s_waitcnt lgkmcnt(5)
	v_mfma_f32_32x32x16_bf16 v[48:63], a[0:3], a[8:11], v[48:63]
	s_and_b32 m0, s32, 7
	s_lshl_b32 m0, m0, 12
	s_add_i32 m0, m0, 0x18c00
	s_nop 0
	global_load_lds_dwordx4 v[176:177], off
	v_mfma_f32_32x32x16_bf16 v[32:47], a[4:7], a[8:11], v[32:47]
	s_waitcnt lgkmcnt(4)
	v_mfma_f32_32x32x16_bf16 v[16:31], a[0:3], a[12:15], v[16:31]
	v_mfma_f32_32x32x16_bf16 v[0:15], a[4:7], a[12:15], v[0:15]
	s_and_b32 m0, s32, 7
	s_lshl_b32 m0, m0, 11
	s_add_i32 m0, m0, 0x20000
	s_nop 0
	global_load_lds_dwordx4 v[178:179], off
	s_nop 0
	s_nop 0
	s_nop 0
	s_nop 0
	s_waitcnt lgkmcnt(1)
	v_mfma_f32_32x32x16_bf16 v[48:63], a[16:19], a[24:27], v[48:63]
	v_mfma_f32_32x32x16_bf16 v[32:47], a[20:23], a[24:27], v[32:47]
	s_and_b32 m0, s32, 7
	s_lshl_b32 m0, m0, 11
	s_add_i32 m0, m0, 0x20400
	s_nop 0
	global_load_lds_dwordx4 v[180:181], off
	s_waitcnt vmcnt(6)
	s_waitcnt lgkmcnt(0)
	s_barrier
	ds_read_b128 a[12:15], v82 offset:53248
	ds_read_b128 a[8:11], v82 offset:49152
	ds_read_b128 a[4:7], v90
	ds_read_b128 a[0:3], v92
	s_nop 0
	v_lshl_add_u64 v[160:161], v[68:69], 0, s[28:29]
	s_nop 0
	v_mfma_f32_32x32x16_bf16 v[16:31], a[16:19], a[28:31], v[16:31]
	s_nop 0
	v_lshl_add_u64 v[162:163], v[70:71], 0, s[28:29]
	s_nop 0
	v_cmp_eq_u32_e64 s[0:1], 0, v79
	s_nop 0
	v_lshl_add_u64 v[164:165], v[72:73], 0, s[28:29]
	s_nop 0
	v_mfma_f32_32x32x16_bf16 v[0:15], a[20:23], a[28:31], v[0:15]
	s_and_b32 m0, s32, 7
	s_lshl_b32 m0, m0, 12
	s_add_i32 m0, m0, 0x0
	s_nop 0
	global_load_lds_dwordx4 v[158:159], off
	s_nop 0
	v_lshl_add_u64 v[166:167], v[74:75], 0, s[28:29]
	s_nop 0
	v_readlane_b32 s20, v215, 52
	s_nop 0
	v_lshl_add_u64 v[168:169], v[76:77], 0, s[28:29]
	s_nop 0
	v_readlane_b32 s21, v215, 53
	s_nop 0
	s_nop 0
	s_nop 0
	s_nop 0
	s_nop 0
	ds_read_b128 a[16:19], v93
	ds_read_b128 a[20:23], v91
	ds_read_b128 a[24:27], v84 offset:49152
	ds_read_b128 a[28:31], v84 offset:53248
	s_waitcnt lgkmcnt(4)
	v_mfma_f32_32x32x16_bf16 v[48:63], a[0:3], a[8:11], v[48:63]
	s_mov_b32 s23, 0
	v_mfma_f32_32x32x16_bf16 v[32:47], a[4:7], a[8:11], v[32:47]
	v_mfma_f32_32x32x16_bf16 v[16:31], a[0:3], a[12:15], v[16:31]
	s_and_b32 m0, s32, 7
	s_lshl_b32 m0, m0, 12
	s_add_i32 m0, m0, 0x400
	s_nop 0
	global_load_lds_dwordx4 v[160:161], off
	v_mfma_f32_32x32x16_bf16 v[0:15], a[4:7], a[12:15], v[0:15]
	s_nop 0
	s_nop 0
	s_nop 0
	s_nop 0
	ds_read_b128 a[0:3], v95
	ds_read_b128 a[4:7], v94
	ds_read_b128 a[8:11], v86 offset:49152
	ds_read_b128 a[12:15], v86 offset:53248
	s_waitcnt lgkmcnt(5)
	v_mfma_f32_32x32x16_bf16 v[48:63], a[16:19], a[24:27], v[48:63]
	v_mfma_f32_32x32x16_bf16 v[32:47], a[20:23], a[24:27], v[32:47]
	s_and_b32 m0, s32, 7
	s_lshl_b32 m0, m0, 12
	s_add_i32 m0, m0, 0x800
	s_nop 0
	global_load_lds_dwordx4 v[162:163], off
	s_waitcnt lgkmcnt(4)
	v_mfma_f32_32x32x16_bf16 v[16:31], a[16:19], a[28:31], v[16:31]
	v_mfma_f32_32x32x16_bf16 v[0:15], a[20:23], a[28:31], v[0:15]
	s_nop 0
	s_nop 0
	s_nop 0
	s_nop 0
	ds_read_b128 a[16:19], v97
	ds_read_b128 a[20:23], v96
	ds_read_b128 a[24:27], v88 offset:49152
	ds_read_b128 a[28:31], v88 offset:53248
	s_waitcnt lgkmcnt(5)
	v_mfma_f32_32x32x16_bf16 v[48:63], a[0:3], a[8:11], v[48:63]
	s_and_b32 m0, s32, 7
	s_lshl_b32 m0, m0, 12
	s_add_i32 m0, m0, 0xc00
	s_nop 0
	global_load_lds_dwordx4 v[164:165], off
	v_mfma_f32_32x32x16_bf16 v[32:47], a[4:7], a[8:11], v[32:47]
	s_waitcnt lgkmcnt(4)
	v_mfma_f32_32x32x16_bf16 v[16:31], a[0:3], a[12:15], v[16:31]
	v_mfma_f32_32x32x16_bf16 v[0:15], a[4:7], a[12:15], v[0:15]
	s_and_b32 m0, s32, 7
	s_lshl_b32 m0, m0, 11
	s_add_i32 m0, m0, 0x8000
	s_nop 0
	global_load_lds_dwordx4 v[166:167], off
	s_nop 0
	s_nop 0
	s_nop 0
	s_nop 0
	s_waitcnt lgkmcnt(1)
	v_mfma_f32_32x32x16_bf16 v[48:63], a[16:19], a[24:27], v[48:63]
	v_mfma_f32_32x32x16_bf16 v[32:47], a[20:23], a[24:27], v[32:47]
	s_and_b32 m0, s32, 7
	s_lshl_b32 m0, m0, 11
	s_add_i32 m0, m0, 0x8400
	s_nop 0
	global_load_lds_dwordx4 v[168:169], off
	s_waitcnt vmcnt(6)
	s_waitcnt lgkmcnt(0)
	s_barrier
	ds_read_b128 a[12:15], v101
	ds_read_b128 a[8:11], v100
	ds_read_b128 a[4:7], v99
	ds_read_b128 a[0:3], v98
	v_mfma_f32_32x32x16_bf16 v[16:31], a[16:19], a[28:31], v[16:31]
	v_mfma_f32_32x32x16_bf16 v[0:15], a[20:23], a[28:31], v[0:15]
	s_nop 0
	s_nop 0
	s_nop 0
	s_nop 0
	ds_read_b128 a[16:19], v102
	ds_read_b128 a[20:23], v103
	ds_read_b128 a[24:27], v104
	ds_read_b128 a[28:31], v105
	s_waitcnt lgkmcnt(4)
	v_mfma_f32_32x32x16_bf16 v[48:63], a[0:3], a[8:11], v[48:63]
	v_mfma_f32_32x32x16_bf16 v[32:47], a[4:7], a[8:11], v[32:47]
	v_mfma_f32_32x32x16_bf16 v[16:31], a[0:3], a[12:15], v[16:31]
	v_mfma_f32_32x32x16_bf16 v[0:15], a[4:7], a[12:15], v[0:15]
	s_nop 0
	s_nop 0
	s_nop 0
	s_nop 0
	ds_read_b128 a[0:3], v106
	ds_read_b128 a[4:7], v107
	ds_read_b128 a[8:11], v108
	ds_read_b128 a[12:15], v109
	s_waitcnt lgkmcnt(5)
	v_mfma_f32_32x32x16_bf16 v[48:63], a[16:19], a[24:27], v[48:63]
	v_mfma_f32_32x32x16_bf16 v[32:47], a[20:23], a[24:27], v[32:47]
	s_waitcnt lgkmcnt(4)
	v_mfma_f32_32x32x16_bf16 v[16:31], a[16:19], a[28:31], v[16:31]
	v_mfma_f32_32x32x16_bf16 v[0:15], a[20:23], a[28:31], v[0:15]
	s_nop 0
	s_nop 0
	s_nop 0
	s_nop 0
	ds_read_b128 a[16:19], v110
	ds_read_b128 a[20:23], v111
	ds_read_b128 a[24:27], v112
	ds_read_b128 a[28:31], v113
	s_waitcnt lgkmcnt(5)
	v_mfma_f32_32x32x16_bf16 v[48:63], a[0:3], a[8:11], v[48:63]
	v_mfma_f32_32x32x16_bf16 v[32:47], a[4:7], a[8:11], v[32:47]
	s_waitcnt lgkmcnt(4)
	v_mfma_f32_32x32x16_bf16 v[16:31], a[0:3], a[12:15], v[16:31]
	v_mfma_f32_32x32x16_bf16 v[0:15], a[4:7], a[12:15], v[0:15]
	s_nop 0
	s_nop 0
	s_nop 0
	s_nop 0
	s_waitcnt lgkmcnt(1)
	v_mfma_f32_32x32x16_bf16 v[48:63], a[16:19], a[24:27], v[48:63]
	v_mfma_f32_32x32x16_bf16 v[32:47], a[20:23], a[24:27], v[32:47]
	s_waitcnt vmcnt(0)
	s_waitcnt lgkmcnt(0)
	s_barrier
	ds_read_b128 a[12:15], v82 offset:4096
	ds_read_b128 a[8:11], v82
	ds_read_b128 a[4:7], v83 offset:36864
	ds_read_b128 a[0:3], v83 offset:32768
	v_mfma_f32_32x32x16_bf16 v[16:31], a[16:19], a[28:31], v[16:31]
	v_mfma_f32_32x32x16_bf16 v[0:15], a[20:23], a[28:31], v[0:15]
	s_nop 0
	s_nop 0
	s_nop 0
	s_nop 0
	ds_read_b128 a[16:19], v85 offset:32768
	ds_read_b128 a[20:23], v85 offset:36864
	ds_read_b128 a[24:27], v84
	ds_read_b128 a[28:31], v84 offset:4096
	s_waitcnt lgkmcnt(4)
	v_mfma_f32_32x32x16_bf16 v[48:63], a[0:3], a[8:11], v[48:63]
	v_mfma_f32_32x32x16_bf16 v[32:47], a[4:7], a[8:11], v[32:47]
	v_mfma_f32_32x32x16_bf16 v[16:31], a[0:3], a[12:15], v[16:31]
	v_mfma_f32_32x32x16_bf16 v[0:15], a[4:7], a[12:15], v[0:15]
	s_nop 0
	s_nop 0
	s_nop 0
	s_nop 0
	ds_read_b128 a[0:3], v87 offset:32768
	ds_read_b128 a[4:7], v87 offset:36864
	ds_read_b128 a[8:11], v86
	ds_read_b128 a[12:15], v86 offset:4096
	s_waitcnt lgkmcnt(5)
	v_mfma_f32_32x32x16_bf16 v[48:63], a[16:19], a[24:27], v[48:63]
	v_mfma_f32_32x32x16_bf16 v[32:47], a[20:23], a[24:27], v[32:47]
	s_waitcnt lgkmcnt(4)
	v_mfma_f32_32x32x16_bf16 v[16:31], a[16:19], a[28:31], v[16:31]
	v_mfma_f32_32x32x16_bf16 v[0:15], a[20:23], a[28:31], v[0:15]
	s_nop 0
	s_nop 0
	s_nop 0
	s_waitcnt lgkmcnt(1)
	v_mfma_f32_32x32x16_bf16 v[48:63], a[0:3], a[8:11], v[48:63]
	v_mfma_f32_32x32x16_bf16 v[32:47], a[4:7], a[8:11], v[32:47]
	s_nop 0
	s_waitcnt lgkmcnt(0)
	v_mfma_f32_32x32x16_bf16 v[0:15], a[4:7], a[12:15], v[0:15]
	v_mfma_f32_32x32x16_bf16 v[16:31], a[0:3], a[12:15], v[16:31]
	ds_read_b128 v[66:69], v89 offset:32768
	ds_read_b128 v[70:73], v88
	ds_read_b128 v[74:77], v89 offset:36864
	ds_read_b128 v[82:85], v88 offset:4096
	s_waitcnt lgkmcnt(0)
	s_barrier
	s_waitcnt lgkmcnt(0)
	v_mfma_f32_32x32x16_bf16 v[48:63], v[66:69], v[70:73], v[48:63]
	v_mfma_f32_32x32x16_bf16 v[32:47], v[74:77], v[70:73], v[32:47]
	s_nop 10
	ds_write_b128 v64, v[48:51]
	ds_write_b128 v64, v[52:55] offset:32
	ds_write_b128 v64, v[56:59] offset:64
	ds_write_b128 v64, v[60:63] offset:96
	ds_write_b128 v64, v[32:35] offset:128
	v_mfma_f32_32x32x16_bf16 v[0:15], v[74:77], v[82:85], v[0:15]
	v_mfma_f32_32x32x16_bf16 v[16:31], v[66:69], v[82:85], v[16:31]
	ds_write_b128 v64, v[36:39] offset:160
	ds_write_b128 v64, v[40:43] offset:192
	ds_write_b128 v64, v[44:47] offset:224
	s_nop 8
	ds_write_b128 v64, v[16:19] offset:16896
	ds_write_b128 v64, v[20:23] offset:16928
	ds_write_b128 v64, v[24:27] offset:16960
	ds_write_b128 v64, v[28:31] offset:16992
	ds_write_b128 v64, v[0:3] offset:17024
	ds_write_b128 v64, v[4:7] offset:17056
	ds_write_b128 v64, v[8:11] offset:17088
	ds_write_b128 v64, v[12:15] offset:17120
	s_waitcnt lgkmcnt(0)
	s_barrier
	v_lshl_or_b32 v0, v79, 2, s31
	v_ashrrev_i32_e32 v1, 31, v0
	v_lshl_add_u32 v4, v79, 4, 0
	v_lshl_add_u64 v[6:7], v[0:1], 2, s[92:93]
	v_lshl_add_u64 v[8:9], v[0:1], 1, s[20:21]
	s_branch .LBB0_161

.LBB0_747:
	v_mov_b32_e32 v78, v133
	s_lshl_b32 s2, s2, 8
	s_bfe_u32 s32, s2, 0x30008
	s_lshl_b32 s32, s32, 15
	v_ashrrev_i32_e32 v6, 6, v78
	v_bfe_u32 v7, v78, 3, 3
	v_lshl_or_b32 v8, v6, 5, v7
	v_add_u32_e32 v0, s2, v8
	s_waitcnt lgkmcnt(0)
	v_ashrrev_i32_e32 v1, 31, v0
	v_lshlrev_b64 v[2:3], 11, v[0:1]
	v_bfe_u32 v1, v78, 4, 2
	v_readlane_b32 s0, v215, 52
	v_xor_b32_e32 v1, v1, v78
	v_readlane_b32 s1, v215, 53
	v_lshlrev_b32_e32 v1, 4, v1
	v_and_b32_e32 v64, 0x70, v1
	v_lshl_add_u64 v[2:3], s[0:1], 0, v[2:3]
	v_or_b32_e32 v1, 8, v8
	v_lshl_add_u64 v[66:67], v[2:3], 0, v[64:65]
	v_add_u32_e32 v2, s2, v1
	v_lshrrev_b32_e32 v1, 1, v1
	v_xor_b32_e32 v1, v1, v78
	v_ashrrev_i32_e32 v3, 31, v2
	v_lshlrev_b32_e32 v1, 4, v1
	v_or_b32_e32 v0, 16, v0
	v_lshlrev_b64 v[2:3], 11, v[2:3]
	v_and_b32_e32 v4, 0x70, v1
	v_ashrrev_i32_e32 v1, 31, v0
	v_lshl_add_u64 v[2:3], s[0:1], 0, v[2:3]
	v_mov_b32_e32 v5, v65
	v_lshlrev_b64 v[0:1], 11, v[0:1]
	v_lshl_add_u64 v[68:69], v[2:3], 0, v[4:5]
	v_lshl_add_u64 v[0:1], s[0:1], 0, v[0:1]
	v_or_b32_e32 v2, 24, v8
	v_lshl_add_u64 v[70:71], v[0:1], 0, v[64:65]
	v_add_u32_e32 v0, s2, v2
	v_lshrrev_b32_e32 v2, 1, v2
	v_ashrrev_i32_e32 v1, 31, v0
	v_xor_b32_e32 v2, v2, v78
	v_lshlrev_b64 v[0:1], 11, v[0:1]
	v_lshlrev_b32_e32 v2, 4, v2
	v_lshl_add_u64 v[0:1], s[0:1], 0, v[0:1]
	v_and_b32_e32 v2, 0x70, v2
	v_mov_b32_e32 v3, v65
	v_lshl_add_u64 v[72:73], v[0:1], 0, v[2:3]
	v_lshl_or_b32 v2, v6, 4, v7
	v_add_u32_e32 v0, s20, v2
	v_lshlrev_b32_e32 v3, 12, v6
	v_ashrrev_i32_e32 v1, 31, v0
	v_add_u32_e32 v131, 0, v3
	v_lshlrev_b64 v[0:1], 11, v[0:1]
	s_waitcnt vmcnt(0)
	v_readfirstlane_b32 s40, v131
	v_add_u32_e32 v130, 0x400, v131
	v_lshl_add_u64 v[0:1], s[96:97], 0, v[0:1]
	v_or_b32_e32 v2, 8, v2
	s_waitcnt lgkmcnt(0)
	s_barrier
	s_mov_b32 m0, s40
	v_readfirstlane_b32 s41, v130
	v_add_u32_e32 v128, 0x800, v131
	v_lshlrev_b32_e32 v5, 11, v6
	v_and_b32_e32 v79, 1, v6
	v_lshl_add_u64 v[74:75], v[0:1], 0, v[64:65]
	v_add_u32_e32 v0, s20, v2
	v_lshrrev_b32_e32 v2, 1, v2
	global_load_lds_dwordx4 v[66:67], off
	s_mov_b32 m0, s41
	v_readfirstlane_b32 s42, v128
	v_add_u32_e32 v126, 0xc00, v131
	v_add_u32_e32 v6, 0, v5
	v_ashrrev_i32_e32 v1, 31, v0
	v_xor_b32_e32 v2, v2, v78
	global_load_lds_dwordx4 v[68:69], off
	s_mov_b32 m0, s42
	v_readfirstlane_b32 s43, v126
	v_add_u32_e32 v129, 0x8000, v6
	v_lshlrev_b64 v[0:1], 11, v[0:1]
	v_lshlrev_b32_e32 v2, 4, v2
	global_load_lds_dwordx4 v[70:71], off
	s_mov_b32 m0, s43
	v_readfirstlane_b32 s44, v129
	v_add_u32_e32 v127, 0x8400, v6
	v_lshl_add_u64 v[0:1], s[96:97], 0, v[0:1]
	v_and_b32_e32 v64, 0x70, v2
	global_load_lds_dwordx4 v[72:73], off
	s_mov_b32 m0, s44
	v_readfirstlane_b32 s45, v127
	v_add_u32_e32 v125, 0xc000, v131
	v_lshl_add_u64 v[76:77], v[0:1], 0, v[64:65]
	global_load_lds_dwordx4 v[74:75], off
	s_mov_b32 m0, s45
	s_lshr_b32 s0, s32, 15
	s_add_i32 s0, s0, 0
	s_sub_i32 s1, s0, 15
	s_cmp_ge_u32 s0, 15
	s_cselect_b32 s0, s1, s0
	s_add_i32 s0, s0, 1
	s_lshl_b32 s0, s0, 7
	s_mov_b32 s1, 0
	v_readfirstlane_b32 s29, v125
	v_add_u32_e32 v120, 0xc400, v131
	global_load_lds_dwordx4 v[76:77], off
	v_lshl_add_u64 v[0:1], v[66:67], 0, s[0:1]
	s_mov_b32 m0, s29
	v_readfirstlane_b32 s33, v120
	v_add_u32_e32 v121, 0xc800, v131
	global_load_lds_dwordx4 v[0:1], off
	v_lshl_add_u64 v[0:1], v[68:69], 0, s[0:1]
	s_mov_b32 m0, s33
	v_readfirstlane_b32 s36, v121
	v_add_u32_e32 v122, 0xcc00, v131
	global_load_lds_dwordx4 v[0:1], off
	v_lshl_add_u64 v[0:1], v[70:71], 0, s[0:1]
	s_mov_b32 m0, s36
	v_readfirstlane_b32 s37, v122
	v_add_u32_e32 v123, s85, v5
	global_load_lds_dwordx4 v[0:1], off
	v_lshl_add_u64 v[0:1], v[72:73], 0, s[0:1]
	s_mov_b32 m0, s37
	v_readfirstlane_b32 s38, v123
	v_add_u32_e32 v124, 0x14400, v6
	global_load_lds_dwordx4 v[0:1], off
	v_lshl_add_u64 v[0:1], v[74:75], 0, s[0:1]
	s_mov_b32 m0, s38
	v_readfirstlane_b32 s39, v124
	global_load_lds_dwordx4 v[0:1], off
	v_lshl_add_u64 v[0:1], v[76:77], 0, s[0:1]
	s_mov_b32 m0, s39
	v_lshrrev_b32_e32 v2, 1, v78
	v_bfe_u32 v64, v78, 5, 1
	global_load_lds_dwordx4 v[0:1], off
	v_add_u32_e32 v119, s3, v3
	v_bitop3_b32 v0, v2, v64, 7 bitop3:0x6c
	s_waitcnt vmcnt(6)
	s_lshr_b32 s30, s32, 15
	s_add_i32 s30, s30, 1
	s_sub_i32 s31, s30, 15
	s_cmp_ge_u32 s30, 15
	s_cselect_b32 s30, s31, s30
	s_add_i32 s30, s30, 1
	s_lshl_b32 s30, s30, 7
	s_mov_b32 s31, 0
	v_readfirstlane_b32 s0, v119
	v_add_u32_e32 v114, 0x400, v119
	v_lshlrev_b32_e32 v132, 4, v0
	s_waitcnt lgkmcnt(0)
	s_barrier
	v_lshl_add_u64 v[0:1], v[66:67], 0, s[30:31]
	s_mov_b32 m0, s0
	v_readfirstlane_b32 s1, v114
	v_add_u32_e32 v115, 0x800, v119
	global_load_lds_dwordx4 v[0:1], off
	v_lshl_add_u64 v[0:1], v[68:69], 0, s[30:31]
	s_mov_b32 m0, s1
	v_readfirstlane_b32 s21, v115
	v_add_u32_e32 v116, 0xc00, v119
	v_readlane_b32 s23, v212, 31
	v_and_b32_e32 v81, 31, v78
	global_load_lds_dwordx4 v[0:1], off
	v_lshl_add_u64 v[0:1], v[70:71], 0, s[30:31]
	s_mov_b32 m0, s21
	v_readfirstlane_b32 s22, v116
	v_add_u32_e32 v117, s23, v5
	v_add_u32_e32 v2, s3, v5
	v_lshlrev_b32_e32 v4, 7, v81
	global_load_lds_dwordx4 v[0:1], off
	v_lshl_add_u64 v[0:1], v[72:73], 0, s[30:31]
	s_mov_b32 m0, s22
	v_readfirstlane_b32 s23, v117
	v_add_u32_e32 v118, 0x8400, v2
	v_lshl_or_b32 v102, v79, 13, v4
	global_load_lds_dwordx4 v[0:1], off
	v_lshl_add_u64 v[0:1], v[74:75], 0, s[30:31]
	s_mov_b32 m0, s23
	v_readfirstlane_b32 s28, v118
	global_load_lds_dwordx4 v[0:1], off
	v_lshl_add_u64 v[0:1], v[76:77], 0, s[30:31]
	s_mov_b32 m0, s28
	v_add_u32_e32 v100, 0, v102
	global_load_lds_dwordx4 v[0:1], off
	v_add_u32_e32 v85, v100, v132
	v_ashrrev_i32_e32 v80, 7, v78
	ds_read_b128 v[0:3], v85 offset:32768
	ds_read_b128 v[86:89], v85 offset:36864
	v_lshl_or_b32 v134, v80, 13, v4
	v_add_u32_e32 v101, 0, v134
	v_add_u32_e32 v84, v101, v132
	ds_read_b128 v[4:7], v84
	v_bfe_u32 v103, v78, 1, 3
	s_waitcnt lgkmcnt(0)
	v_lshrrev_b32_e32 v182, 6, v133
	v_or_b32_e32 v182, s32, v182
	s_nop 0
	v_readfirstlane_b32 s32, v182
	v_mfma_f32_32x32x16_bf16 v[48:63], v[0:3], v[4:7], 0
	v_bitop3_b32 v8, v64, v103, 2 bitop3:0x36
	v_lshlrev_b32_e32 v135, 4, v8
	v_add_u32_e32 v83, v100, v135
	ds_read_b128 v[8:11], v83 offset:32768
	ds_read_b128 v[90:93], v83 offset:36864
	v_add_u32_e32 v82, v101, v135
	ds_read_b128 v[12:15], v82
	ds_read_b128 v[94:97], v82 offset:4096
	s_waitcnt vmcnt(12)
	v_mfma_f32_32x32x16_bf16 v[32:47], v[86:89], v[4:7], 0
	ds_read_b128 v[4:7], v84 offset:4096
	s_lshr_b32 s30, s32, 15
	s_add_i32 s30, s30, 2
	s_sub_i32 s31, s30, 15
	s_cmp_ge_u32 s30, 15
	s_cselect_b32 s30, s31, s30
	s_add_i32 s30, s30, 1
	s_lshl_b32 s30, s30, 7
	s_mov_b32 s31, 0
	s_nop 0
	v_or_b32_e32 v143, 0x8000, v102
	v_or_b32_e32 v144, 0x9000, v102
	v_add_u32_e32 v145, s3, v134
	s_mov_b64 s[80:81], 0x200
	s_waitcnt lgkmcnt(0)
	v_mfma_f32_32x32x16_bf16 v[16:31], v[0:3], v[4:7], 0
	v_mfma_f32_32x32x16_bf16 v[48:63], v[8:11], v[12:15], v[48:63]
	v_mfma_f32_32x32x16_bf16 v[32:47], v[90:93], v[12:15], v[32:47]
	v_mfma_f32_32x32x16_bf16 v[16:31], v[8:11], v[94:97], v[16:31]
	v_mfma_f32_32x32x16_bf16 v[0:15], v[86:89], v[4:7], 0
	v_bitop3_b32 v86, v64, v103, 4 bitop3:0x36
	v_lshlrev_b32_e32 v138, 4, v86
	v_add_u32_e32 v87, v100, v138
	v_add_u32_e32 v86, v101, v138
	v_mfma_f32_32x32x16_bf16 v[0:15], v[90:93], v[94:97], v[0:15]
	ds_read_b128 v[88:91], v87 offset:32768
	ds_read_b128 v[92:95], v86
	ds_read_b128 v[96:99], v87 offset:36864
	s_waitcnt lgkmcnt(1)
	v_mfma_f32_32x32x16_bf16 v[48:63], v[88:91], v[92:95], v[48:63]
	s_waitcnt lgkmcnt(0)
	v_mfma_f32_32x32x16_bf16 v[32:47], v[96:99], v[92:95], v[32:47]
	ds_read_b128 v[92:95], v86 offset:4096
	s_waitcnt lgkmcnt(0)
	v_mfma_f32_32x32x16_bf16 v[16:31], v[88:91], v[92:95], v[16:31]
	v_bitop3_b32 v88, v64, v103, 6 bitop3:0x36
	v_lshlrev_b32_e32 v142, 4, v88
	v_add_u32_e32 v89, v100, v142
	v_add_u32_e32 v88, v101, v142
	v_mfma_f32_32x32x16_bf16 v[0:15], v[96:99], v[92:95], v[0:15]
	ds_read_b128 v[90:93], v89 offset:32768
	ds_read_b128 v[94:97], v88
	ds_read_b128 v[98:101], v89 offset:36864
	s_waitcnt lgkmcnt(1)
	v_mfma_f32_32x32x16_bf16 v[48:63], v[90:93], v[94:97], v[48:63]
	s_waitcnt lgkmcnt(0)
	v_mfma_f32_32x32x16_bf16 v[32:47], v[98:101], v[94:97], v[32:47]
	ds_read_b128 v[94:97], v88 offset:4096
	s_waitcnt vmcnt(6)
	s_waitcnt lgkmcnt(0)
	s_barrier
	s_waitcnt lgkmcnt(0)
	v_mfma_f32_32x32x16_bf16 v[16:31], v[90:93], v[94:97], v[16:31]
	v_lshl_add_u64 v[158:159], v[66:67], 0, s[30:31]
	s_nop 0
	v_lshl_add_u64 v[160:161], v[68:69], 0, s[30:31]
	s_nop 0
	s_nop 0
	s_nop 0
	v_lshl_add_u64 v[162:163], v[70:71], 0, s[30:31]
	s_nop 0
	v_mfma_f32_32x32x16_bf16 v[0:15], v[98:101], v[94:97], v[0:15]
	s_and_b32 m0, s32, 7
	s_lshl_b32 m0, m0, 12
	s_add_i32 m0, m0, 0x0
	s_nop 0
	global_load_lds_dwordx4 v[158:159], off
	s_nop 0
	v_lshl_add_u64 v[164:165], v[72:73], 0, s[30:31]
	s_nop 0
	s_nop 0
	s_nop 0
	v_lshl_add_u64 v[166:167], v[74:75], 0, s[30:31]
	s_nop 0
	s_nop 0
	s_nop 0
	v_lshl_add_u64 v[168:169], v[76:77], 0, s[30:31]
	s_nop 0
	s_add_i32 s30, 0, 0xc000
	s_nop 0
	v_add_u32_e32 v90, s30, v132
	v_add_u32_e32 v91, v90, v143
	v_add_u32_e32 v90, v90, v144
	ds_read_b128 v[92:95], v91
	ds_read_b128 v[96:99], v84 offset:49152
	ds_read_b128 v[100:103], v90
	ds_read_b128 v[150:153], v84 offset:53248
	s_waitcnt lgkmcnt(1)
	v_mfma_f32_32x32x16_bf16 v[48:63], v[92:95], v[96:99], v[48:63]
	s_nop 0
	v_mfma_f32_32x32x16_bf16 v[32:47], v[100:103], v[96:99], v[32:47]
	s_waitcnt lgkmcnt(0)
	v_mfma_f32_32x32x16_bf16 v[16:31], v[92:95], v[150:153], v[16:31]
	s_and_b32 m0, s32, 7
	s_lshl_b32 m0, m0, 12
	s_add_i32 m0, m0, 0x400
	s_nop 0
	global_load_lds_dwordx4 v[160:161], off
	v_add_u32_e32 v92, s30, v135
	v_add_u32_e32 v94, v92, v143
	v_add_u32_e32 v92, v92, v144
	v_add_u32_e32 v93, s30, v138
	v_add_u32_e32 v95, v93, v143
	v_add_u32_e32 v93, v93, v144
	v_mfma_f32_32x32x16_bf16 v[0:15], v[100:103], v[150:153], v[0:15]
	ds_read_b128 v[96:99], v94
	ds_read_b128 v[100:103], v82 offset:49152
	ds_read_b128 v[104:107], v92
	ds_read_b128 v[154:157], v82 offset:53248
	s_waitcnt lgkmcnt(1)
	v_mfma_f32_32x32x16_bf16 v[48:63], v[96:99], v[100:103], v[48:63]
	v_mfma_f32_32x32x16_bf16 v[32:47], v[104:107], v[100:103], v[32:47]
	s_and_b32 m0, s32, 7
	s_lshl_b32 m0, m0, 12
	s_add_i32 m0, m0, 0x800
	s_nop 0
	global_load_lds_dwordx4 v[162:163], off
	s_waitcnt lgkmcnt(0)
	v_mfma_f32_32x32x16_bf16 v[16:31], v[96:99], v[154:157], v[16:31]
	v_mfma_f32_32x32x16_bf16 v[0:15], v[104:107], v[154:157], v[0:15]
	ds_read_b128 v[96:99], v95
	ds_read_b128 v[100:103], v86 offset:49152
	ds_read_b128 v[104:107], v93
	ds_read_b128 v[150:153], v86 offset:53248
	s_waitcnt lgkmcnt(1)
	v_mfma_f32_32x32x16_bf16 v[48:63], v[96:99], v[100:103], v[48:63]
	s_and_b32 m0, s32, 7
	s_lshl_b32 m0, m0, 12
	s_add_i32 m0, m0, 0xc00
	s_nop 0
	global_load_lds_dwordx4 v[164:165], off
	v_mfma_f32_32x32x16_bf16 v[32:47], v[104:107], v[100:103], v[32:47]
	s_waitcnt lgkmcnt(0)
	v_mfma_f32_32x32x16_bf16 v[16:31], v[96:99], v[150:153], v[16:31]
	v_add_u32_e32 v96, s30, v142
	v_add_u32_e32 v97, v96, v143
	v_add_u32_e32 v96, v96, v144
	s_lshr_b32 s30, s32, 15
	s_add_i32 s30, s30, 3
	s_sub_i32 s31, s30, 15
	s_cmp_ge_u32 s30, 15
	s_cselect_b32 s30, s31, s30
	s_add_i32 s30, s30, 1
	s_lshl_b32 s30, s30, 7
	s_mov_b32 s31, 0
	v_mfma_f32_32x32x16_bf16 v[0:15], v[104:107], v[150:153], v[0:15]
	s_and_b32 m0, s32, 7
	s_lshl_b32 m0, m0, 11
	s_add_i32 m0, m0, 0x8000
	s_nop 0
	global_load_lds_dwordx4 v[166:167], off
	ds_read_b128 v[98:101], v97
	ds_read_b128 v[102:105], v88 offset:49152
	ds_read_b128 v[106:109], v96
	ds_read_b128 v[154:157], v88 offset:53248
	s_waitcnt lgkmcnt(1)
	v_mfma_f32_32x32x16_bf16 v[48:63], v[98:101], v[102:105], v[48:63]
	v_mfma_f32_32x32x16_bf16 v[32:47], v[106:109], v[102:105], v[32:47]
	s_and_b32 m0, s32, 7
	s_lshl_b32 m0, m0, 11
	s_add_i32 m0, m0, 0x8400
	s_nop 0
	global_load_lds_dwordx4 v[168:169], off
	s_waitcnt vmcnt(6)
	s_waitcnt lgkmcnt(0)
	s_barrier
	s_waitcnt lgkmcnt(0)
	v_mfma_f32_32x32x16_bf16 v[16:31], v[98:101], v[154:157], v[16:31]
	v_lshl_add_u64 v[170:171], v[66:67], 0, s[30:31]
	s_nop 0
	v_lshl_add_u64 v[172:173], v[68:69], 0, s[30:31]
	s_nop 0
	v_add_u32_e32 v101, s3, v132
	s_nop 0
	v_lshl_add_u64 v[174:175], v[70:71], 0, s[30:31]
	s_nop 0
	v_mfma_f32_32x32x16_bf16 v[0:15], v[106:109], v[154:157], v[0:15]
	s_and_b32 m0, s32, 7
	s_lshl_b32 m0, m0, 12
	s_add_i32 m0, m0, 0xc000
	s_nop 0
	global_load_lds_dwordx4 v[170:171], off
	s_nop 0
	v_lshl_add_u64 v[176:177], v[72:73], 0, s[30:31]
	s_nop 0
	v_add_u32_e32 v100, v145, v132
	s_nop 0
	v_lshl_add_u64 v[178:179], v[74:75], 0, s[30:31]
	s_nop 0
	v_or_b32_e32 v132, 0x1000, v134
	s_nop 0
	v_lshl_add_u64 v[180:181], v[76:77], 0, s[30:31]
	s_nop 0
	s_lshr_b32 s30, s32, 15
	s_add_i32 s30, s30, 4
	s_sub_i32 s31, s30, 15
	s_cmp_ge_u32 s30, 15
	s_cselect_b32 s30, s31, s30
	s_add_i32 s30, s30, 1
	s_lshl_b32 s30, s30, 7
	s_mov_b32 s31, 0
	s_nop 0
	v_add_u32_e32 v98, v101, v143
	v_add_u32_e32 v99, v101, v144
	ds_read_b128 v[110:113], v98
	ds_read_b128 v[106:109], v99
	ds_read_b128 v[102:105], v100
	v_add_u32_e32 v101, v101, v132
	ds_read_b128 v[150:153], v101
	s_waitcnt lgkmcnt(1)
	v_mfma_f32_32x32x16_bf16 v[48:63], v[110:113], v[102:105], v[48:63]
	s_nop 0
	v_mfma_f32_32x32x16_bf16 v[32:47], v[106:109], v[102:105], v[32:47]
	s_waitcnt lgkmcnt(0)
	v_mfma_f32_32x32x16_bf16 v[16:31], v[110:113], v[150:153], v[16:31]
	s_and_b32 m0, s32, 7
	s_lshl_b32 m0, m0, 12
	s_add_i32 m0, m0, 0xc400
	s_nop 0
	global_load_lds_dwordx4 v[172:173], off
	v_mfma_f32_32x32x16_bf16 v[0:15], v[106:109], v[150:153], v[0:15]
	v_add_u32_e32 v105, s3, v135
	v_add_u32_e32 v103, v105, v143
	v_add_u32_e32 v102, v105, v144
	ds_read_b128 v[106:109], v103
	v_add_u32_e32 v104, v145, v135
	ds_read_b128 v[134:137], v102
	ds_read_b128 v[110:113], v104
	v_add_u32_e32 v105, v105, v132
	ds_read_b128 v[154:157], v105
	s_waitcnt lgkmcnt(1)
	v_mfma_f32_32x32x16_bf16 v[48:63], v[106:109], v[110:113], v[48:63]
	v_mfma_f32_32x32x16_bf16 v[32:47], v[134:137], v[110:113], v[32:47]
	s_and_b32 m0, s32, 7
	s_lshl_b32 m0, m0, 12
	s_add_i32 m0, m0, 0xc800
	s_nop 0
	global_load_lds_dwordx4 v[174:175], off
	s_waitcnt lgkmcnt(0)
	v_mfma_f32_32x32x16_bf16 v[16:31], v[106:109], v[154:157], v[16:31]
	v_add_u32_e32 v109, s3, v138
	v_add_u32_e32 v107, v109, v143
	v_add_u32_e32 v106, v109, v144
	v_add_u32_e32 v108, v145, v138
	ds_read_b128 v[138:141], v106
	v_add_u32_e32 v109, v109, v132
	v_mfma_f32_32x32x16_bf16 v[0:15], v[134:137], v[154:157], v[0:15]
	ds_read_b128 v[110:113], v107
	ds_read_b128 v[134:137], v108
	ds_read_b128 v[150:153], v109
	s_waitcnt lgkmcnt(1)
	v_mfma_f32_32x32x16_bf16 v[48:63], v[110:113], v[134:137], v[48:63]
	s_and_b32 m0, s32, 7
	s_lshl_b32 m0, m0, 12
	s_add_i32 m0, m0, 0xcc00
	s_nop 0
	global_load_lds_dwordx4 v[176:177], off
	v_mfma_f32_32x32x16_bf16 v[32:47], v[138:141], v[134:137], v[32:47]
	s_waitcnt lgkmcnt(0)
	v_mfma_f32_32x32x16_bf16 v[16:31], v[110:113], v[150:153], v[16:31]
	v_add_u32_e32 v113, s3, v142
	v_add_u32_e32 v111, v113, v143
	v_add_u32_e32 v110, v113, v144
	v_add_u32_e32 v112, v145, v142
	ds_read_b128 v[142:145], v110
	v_add_u32_e32 v113, v113, v132
	v_mfma_f32_32x32x16_bf16 v[0:15], v[138:141], v[150:153], v[0:15]
	s_and_b32 m0, s32, 7
	s_lshl_b32 m0, m0, 11
	s_add_i32 m0, m0, 0x14000
	s_nop 0
	global_load_lds_dwordx4 v[178:179], off
	ds_read_b128 v[134:137], v111
	ds_read_b128 v[138:141], v112
	ds_read_b128 v[154:157], v113
	s_waitcnt lgkmcnt(1)
	v_mfma_f32_32x32x16_bf16 v[48:63], v[134:137], v[138:141], v[48:63]
	v_mfma_f32_32x32x16_bf16 v[32:47], v[142:145], v[138:141], v[32:47]
	s_and_b32 m0, s32, 7
	s_lshl_b32 m0, m0, 11
	s_add_i32 m0, m0, 0x14400
	s_nop 0
	global_load_lds_dwordx4 v[180:181], off
	s_waitcnt vmcnt(6)
	s_waitcnt lgkmcnt(0)
	s_barrier
	s_waitcnt lgkmcnt(0)
	v_mfma_f32_32x32x16_bf16 v[16:31], v[134:137], v[154:157], v[16:31]
	v_lshl_add_u64 v[158:159], v[66:67], 0, s[30:31]
	s_nop 0
	v_lshl_add_u64 v[160:161], v[68:69], 0, s[30:31]
	s_nop 0
	s_nop 0
	s_nop 0
	v_lshl_add_u64 v[162:163], v[70:71], 0, s[30:31]
	s_nop 0
	v_mfma_f32_32x32x16_bf16 v[0:15], v[142:145], v[154:157], v[0:15]
	s_and_b32 m0, s32, 7
	s_lshl_b32 m0, m0, 12
	s_add_i32 m0, m0, 0x18000
	s_nop 0
	global_load_lds_dwordx4 v[158:159], off
	s_nop 0
	v_lshl_add_u64 v[164:165], v[72:73], 0, s[30:31]
	s_nop 0
	s_nop 0
	s_nop 0
	v_lshl_add_u64 v[166:167], v[74:75], 0, s[30:31]
	s_nop 0
	s_nop 0
	s_nop 0
	v_lshl_add_u64 v[168:169], v[76:77], 0, s[30:31]
	s_nop 0
	s_lshr_b32 s30, s32, 15
	s_add_i32 s30, s30, 5
	s_sub_i32 s31, s30, 15
	s_cmp_ge_u32 s30, 15
	s_cselect_b32 s30, s31, s30
	s_add_i32 s30, s30, 1
	s_lshl_b32 s30, s30, 7
	s_mov_b32 s31, 0
	s_nop 0
	ds_read_b128 v[134:137], v85 offset:32768
	ds_read_b128 v[138:141], v84
	ds_read_b128 v[142:145], v85 offset:36864
	ds_read_b128 v[150:153], v84 offset:4096
	s_waitcnt lgkmcnt(1)
	v_mfma_f32_32x32x16_bf16 v[48:63], v[134:137], v[138:141], v[48:63]
	s_nop 0
	v_readfirstlane_b32 s40, v119
	v_mfma_f32_32x32x16_bf16 v[32:47], v[142:145], v[138:141], v[32:47]
	s_waitcnt lgkmcnt(0)
	v_mfma_f32_32x32x16_bf16 v[16:31], v[134:137], v[150:153], v[16:31]
	s_and_b32 m0, s32, 7
	s_lshl_b32 m0, m0, 12
	s_add_i32 m0, m0, 0x18400
	s_nop 0
	global_load_lds_dwordx4 v[160:161], off
	v_mfma_f32_32x32x16_bf16 v[0:15], v[142:145], v[150:153], v[0:15]
	ds_read_b128 v[134:137], v83 offset:32768
	ds_read_b128 v[138:141], v82
	ds_read_b128 v[142:145], v83 offset:36864
	ds_read_b128 v[154:157], v82 offset:4096
	s_waitcnt lgkmcnt(1)
	v_mfma_f32_32x32x16_bf16 v[48:63], v[134:137], v[138:141], v[48:63]
	v_mfma_f32_32x32x16_bf16 v[32:47], v[142:145], v[138:141], v[32:47]
	s_and_b32 m0, s32, 7
	s_lshl_b32 m0, m0, 12
	s_add_i32 m0, m0, 0x18800
	s_nop 0
	global_load_lds_dwordx4 v[162:163], off
	s_waitcnt lgkmcnt(0)
	v_mfma_f32_32x32x16_bf16 v[16:31], v[134:137], v[154:157], v[16:31]
	v_mfma_f32_32x32x16_bf16 v[0:15], v[142:145], v[154:157], v[0:15]
	ds_read_b128 v[134:137], v87 offset:32768
	ds_read_b128 v[138:141], v86
	ds_read_b128 v[142:145], v87 offset:36864
	ds_read_b128 v[150:153], v86 offset:4096
	s_waitcnt lgkmcnt(1)
	v_mfma_f32_32x32x16_bf16 v[48:63], v[134:137], v[138:141], v[48:63]
	s_and_b32 m0, s32, 7
	s_lshl_b32 m0, m0, 12
	s_add_i32 m0, m0, 0x18c00
	s_nop 0
	global_load_lds_dwordx4 v[164:165], off
	v_mfma_f32_32x32x16_bf16 v[32:47], v[142:145], v[138:141], v[32:47]
	s_waitcnt lgkmcnt(0)
	v_mfma_f32_32x32x16_bf16 v[16:31], v[134:137], v[150:153], v[16:31]
	v_mfma_f32_32x32x16_bf16 v[0:15], v[142:145], v[150:153], v[0:15]
	s_and_b32 m0, s32, 7
	s_lshl_b32 m0, m0, 11
	s_add_i32 m0, m0, 0x20000
	s_nop 0
	global_load_lds_dwordx4 v[166:167], off
	ds_read_b128 v[134:137], v89 offset:32768
	ds_read_b128 v[138:141], v88
	ds_read_b128 v[142:145], v89 offset:36864
	ds_read_b128 v[154:157], v88 offset:4096
	s_waitcnt lgkmcnt(1)
	v_mfma_f32_32x32x16_bf16 v[48:63], v[134:137], v[138:141], v[48:63]
	v_mfma_f32_32x32x16_bf16 v[32:47], v[142:145], v[138:141], v[32:47]
	s_and_b32 m0, s32, 7
	s_lshl_b32 m0, m0, 11
	s_add_i32 m0, m0, 0x20400
	s_nop 0
	global_load_lds_dwordx4 v[168:169], off
	s_waitcnt vmcnt(6)
	s_waitcnt lgkmcnt(0)
	s_barrier
	s_waitcnt lgkmcnt(0)
	v_mfma_f32_32x32x16_bf16 v[16:31], v[134:137], v[154:157], v[16:31]
	v_lshl_add_u64 v[170:171], v[66:67], 0, s[30:31]
	s_nop 0
	v_lshl_add_u64 v[172:173], v[68:69], 0, s[30:31]
	s_nop 0
	v_readfirstlane_b32 s41, v114
	s_nop 0
	v_lshl_add_u64 v[174:175], v[70:71], 0, s[30:31]
	s_nop 0
	v_mfma_f32_32x32x16_bf16 v[0:15], v[142:145], v[154:157], v[0:15]
	s_and_b32 m0, s32, 7
	s_lshl_b32 m0, m0, 12
	s_add_i32 m0, m0, 0x0
	s_nop 0
	global_load_lds_dwordx4 v[170:171], off
	s_nop 0
	v_lshl_add_u64 v[176:177], v[72:73], 0, s[30:31]
	s_nop 0
	v_readfirstlane_b32 s42, v115
	s_nop 0
	v_lshl_add_u64 v[178:179], v[74:75], 0, s[30:31]
	s_nop 0
	v_readfirstlane_b32 s43, v116
	s_nop 0
	v_lshl_add_u64 v[180:181], v[76:77], 0, s[30:31]
	s_nop 0
	s_lshr_b32 s30, s32, 15
	s_add_i32 s30, s30, 6
	s_sub_i32 s31, s30, 15
	s_cmp_ge_u32 s30, 15
	s_cselect_b32 s30, s31, s30
	s_add_i32 s30, s30, 1
	s_lshl_b32 s30, s30, 7
	s_mov_b32 s31, 0
	s_nop 0
	ds_read_b128 v[134:137], v91
	ds_read_b128 v[138:141], v84 offset:49152
	ds_read_b128 v[142:145], v90
	ds_read_b128 v[150:153], v84 offset:53248
	s_waitcnt lgkmcnt(1)
	v_mfma_f32_32x32x16_bf16 v[48:63], v[134:137], v[138:141], v[48:63]
	s_nop 0
	v_readfirstlane_b32 s29, v125
	v_readfirstlane_b32 s44, v117
	v_readfirstlane_b32 s45, v118
	v_mfma_f32_32x32x16_bf16 v[32:47], v[142:145], v[138:141], v[32:47]
	s_waitcnt lgkmcnt(0)
	v_mfma_f32_32x32x16_bf16 v[16:31], v[134:137], v[150:153], v[16:31]
	s_and_b32 m0, s32, 7
	s_lshl_b32 m0, m0, 12
	s_add_i32 m0, m0, 0x400
	s_nop 0
	global_load_lds_dwordx4 v[172:173], off
	v_mfma_f32_32x32x16_bf16 v[0:15], v[142:145], v[150:153], v[0:15]
	ds_read_b128 v[134:137], v94
	ds_read_b128 v[138:141], v82 offset:49152
	ds_read_b128 v[142:145], v92
	ds_read_b128 v[154:157], v82 offset:53248
	s_waitcnt lgkmcnt(1)
	v_mfma_f32_32x32x16_bf16 v[48:63], v[134:137], v[138:141], v[48:63]
	v_mfma_f32_32x32x16_bf16 v[32:47], v[142:145], v[138:141], v[32:47]
	s_and_b32 m0, s32, 7
	s_lshl_b32 m0, m0, 12
	s_add_i32 m0, m0, 0x800
	s_nop 0
	global_load_lds_dwordx4 v[174:175], off
	s_waitcnt lgkmcnt(0)
	v_mfma_f32_32x32x16_bf16 v[16:31], v[134:137], v[154:157], v[16:31]
	v_mfma_f32_32x32x16_bf16 v[0:15], v[142:145], v[154:157], v[0:15]
	ds_read_b128 v[134:137], v95
	ds_read_b128 v[138:141], v86 offset:49152
	ds_read_b128 v[142:145], v93
	ds_read_b128 v[150:153], v86 offset:53248
	s_waitcnt lgkmcnt(1)
	v_mfma_f32_32x32x16_bf16 v[48:63], v[134:137], v[138:141], v[48:63]
	s_and_b32 m0, s32, 7
	s_lshl_b32 m0, m0, 12
	s_add_i32 m0, m0, 0xc00
	s_nop 0
	global_load_lds_dwordx4 v[176:177], off
	v_mfma_f32_32x32x16_bf16 v[32:47], v[142:145], v[138:141], v[32:47]
	s_waitcnt lgkmcnt(0)
	v_mfma_f32_32x32x16_bf16 v[16:31], v[134:137], v[150:153], v[16:31]
	v_mfma_f32_32x32x16_bf16 v[0:15], v[142:145], v[150:153], v[0:15]
	s_and_b32 m0, s32, 7
	s_lshl_b32 m0, m0, 11
	s_add_i32 m0, m0, 0x8000
	s_nop 0
	global_load_lds_dwordx4 v[178:179], off
	ds_read_b128 v[134:137], v97
	ds_read_b128 v[138:141], v88 offset:49152
	ds_read_b128 v[142:145], v96
	ds_read_b128 v[154:157], v88 offset:53248
	s_waitcnt lgkmcnt(1)
	v_mfma_f32_32x32x16_bf16 v[48:63], v[134:137], v[138:141], v[48:63]
	v_mfma_f32_32x32x16_bf16 v[32:47], v[142:145], v[138:141], v[32:47]
	s_and_b32 m0, s32, 7
	s_lshl_b32 m0, m0, 11
	s_add_i32 m0, m0, 0x8400
	s_nop 0
	global_load_lds_dwordx4 v[180:181], off
	s_waitcnt vmcnt(6)
	s_waitcnt lgkmcnt(0)
	s_barrier
	s_waitcnt lgkmcnt(0)
	v_mfma_f32_32x32x16_bf16 v[16:31], v[134:137], v[154:157], v[16:31]
	v_lshl_add_u64 v[158:159], v[66:67], 0, s[30:31]
	s_nop 0
	v_lshl_add_u64 v[160:161], v[68:69], 0, s[30:31]
	s_nop 0
	v_readfirstlane_b32 s33, v120
	s_nop 0
	v_lshl_add_u64 v[162:163], v[70:71], 0, s[30:31]
	s_nop 0
	v_mfma_f32_32x32x16_bf16 v[0:15], v[142:145], v[154:157], v[0:15]
	s_and_b32 m0, s32, 7
	s_lshl_b32 m0, m0, 12
	s_add_i32 m0, m0, 0xc000
	s_nop 0
	global_load_lds_dwordx4 v[158:159], off
	s_nop 0
	v_lshl_add_u64 v[164:165], v[72:73], 0, s[30:31]
	s_nop 0
	v_readfirstlane_b32 s36, v121
	s_nop 0
	v_lshl_add_u64 v[166:167], v[74:75], 0, s[30:31]
	s_nop 0
	v_readfirstlane_b32 s37, v122
	s_nop 0
	v_lshl_add_u64 v[168:169], v[76:77], 0, s[30:31]
	s_nop 0
	s_lshr_b32 s30, s32, 15
	s_add_i32 s30, s30, 7
	s_sub_i32 s31, s30, 15
	s_cmp_ge_u32 s30, 15
	s_cselect_b32 s30, s31, s30
	s_add_i32 s30, s30, 1
	s_lshl_b32 s30, s30, 7
	s_mov_b32 s31, 0
	s_nop 0
	ds_read_b128 v[134:137], v98
	ds_read_b128 v[138:141], v100
	ds_read_b128 v[142:145], v99
	ds_read_b128 v[150:153], v101
	s_waitcnt lgkmcnt(1)
	v_mfma_f32_32x32x16_bf16 v[48:63], v[134:137], v[138:141], v[48:63]
	s_nop 0
	v_readfirstlane_b32 s0, v131
	v_readfirstlane_b32 s38, v123
	v_readfirstlane_b32 s39, v124
	v_mfma_f32_32x32x16_bf16 v[32:47], v[142:145], v[138:141], v[32:47]
	s_waitcnt lgkmcnt(0)
	v_mfma_f32_32x32x16_bf16 v[16:31], v[134:137], v[150:153], v[16:31]
	s_and_b32 m0, s32, 7
	s_lshl_b32 m0, m0, 12
	s_add_i32 m0, m0, 0xc400
	s_nop 0
	global_load_lds_dwordx4 v[160:161], off
	v_mfma_f32_32x32x16_bf16 v[0:15], v[142:145], v[150:153], v[0:15]
	ds_read_b128 v[134:137], v103
	ds_read_b128 v[138:141], v104
	ds_read_b128 v[142:145], v102
	ds_read_b128 v[154:157], v105
	s_waitcnt lgkmcnt(1)
	v_mfma_f32_32x32x16_bf16 v[48:63], v[134:137], v[138:141], v[48:63]
	v_mfma_f32_32x32x16_bf16 v[32:47], v[142:145], v[138:141], v[32:47]
	s_and_b32 m0, s32, 7
	s_lshl_b32 m0, m0, 12
	s_add_i32 m0, m0, 0xc800
	s_nop 0
	global_load_lds_dwordx4 v[162:163], off
	s_waitcnt lgkmcnt(0)
	v_mfma_f32_32x32x16_bf16 v[16:31], v[134:137], v[154:157], v[16:31]
	v_mfma_f32_32x32x16_bf16 v[0:15], v[142:145], v[154:157], v[0:15]
	ds_read_b128 v[134:137], v107
	ds_read_b128 v[138:141], v108
	ds_read_b128 v[142:145], v106
	ds_read_b128 v[150:153], v109
	s_waitcnt lgkmcnt(1)
	v_mfma_f32_32x32x16_bf16 v[48:63], v[134:137], v[138:141], v[48:63]
	s_and_b32 m0, s32, 7
	s_lshl_b32 m0, m0, 12
	s_add_i32 m0, m0, 0xcc00
	s_nop 0
	global_load_lds_dwordx4 v[164:165], off
	v_mfma_f32_32x32x16_bf16 v[32:47], v[142:145], v[138:141], v[32:47]
	s_waitcnt lgkmcnt(0)
	v_mfma_f32_32x32x16_bf16 v[16:31], v[134:137], v[150:153], v[16:31]
	v_mfma_f32_32x32x16_bf16 v[0:15], v[142:145], v[150:153], v[0:15]
	s_and_b32 m0, s32, 7
	s_lshl_b32 m0, m0, 11
	s_add_i32 m0, m0, 0x14000
	s_nop 0
	global_load_lds_dwordx4 v[166:167], off
	ds_read_b128 v[134:137], v111
	ds_read_b128 v[138:141], v112
	ds_read_b128 v[142:145], v110
	ds_read_b128 v[154:157], v113
	s_waitcnt lgkmcnt(1)
	v_mfma_f32_32x32x16_bf16 v[48:63], v[134:137], v[138:141], v[48:63]
	v_mfma_f32_32x32x16_bf16 v[32:47], v[142:145], v[138:141], v[32:47]
	s_and_b32 m0, s32, 7
	s_lshl_b32 m0, m0, 11
	s_add_i32 m0, m0, 0x14400
	s_nop 0
	global_load_lds_dwordx4 v[168:169], off
	s_waitcnt vmcnt(6)
	s_waitcnt lgkmcnt(0)
	s_barrier
	s_waitcnt lgkmcnt(0)
	v_mfma_f32_32x32x16_bf16 v[16:31], v[134:137], v[154:157], v[16:31]
	v_lshl_add_u64 v[170:171], v[66:67], 0, s[30:31]
	s_nop 0
	v_lshl_add_u64 v[172:173], v[68:69], 0, s[30:31]
	s_nop 0
	v_readfirstlane_b32 s1, v130
	s_nop 0
	v_lshl_add_u64 v[174:175], v[70:71], 0, s[30:31]
	s_nop 0
	v_mfma_f32_32x32x16_bf16 v[0:15], v[142:145], v[154:157], v[0:15]
	s_and_b32 m0, s32, 7
	s_lshl_b32 m0, m0, 12
	s_add_i32 m0, m0, 0x18000
	s_nop 0
	global_load_lds_dwordx4 v[170:171], off
	s_nop 0
	v_lshl_add_u64 v[176:177], v[72:73], 0, s[30:31]
	s_nop 0
	v_readfirstlane_b32 s21, v128
	s_nop 0
	v_lshl_add_u64 v[178:179], v[74:75], 0, s[30:31]
	s_nop 0
	v_readfirstlane_b32 s22, v126
	s_nop 0
	v_lshl_add_u64 v[180:181], v[76:77], 0, s[30:31]
	s_nop 0
	s_lshr_b32 s30, s32, 15
	s_add_i32 s30, s30, 8
	s_sub_i32 s31, s30, 15
	s_cmp_ge_u32 s30, 15
	s_cselect_b32 s30, s31, s30
	s_add_i32 s30, s30, 1
	s_lshl_b32 s30, s30, 7
	s_mov_b32 s31, 0
	s_nop 0
	ds_read_b128 v[134:137], v85 offset:32768
	ds_read_b128 v[138:141], v84
	ds_read_b128 v[142:145], v85 offset:36864
	ds_read_b128 v[150:153], v84 offset:4096
	s_waitcnt lgkmcnt(1)
	v_mfma_f32_32x32x16_bf16 v[48:63], v[134:137], v[138:141], v[48:63]
	s_nop 0
	v_lshl_add_u64 v[160:161], v[68:69], 0, s[30:31]
	v_readfirstlane_b32 s23, v129
	v_lshl_add_u64 v[166:167], v[74:75], 0, s[30:31]
	v_readfirstlane_b32 s28, v127
	v_lshl_add_u64 v[168:169], v[76:77], 0, s[30:31]
	v_mfma_f32_32x32x16_bf16 v[32:47], v[142:145], v[138:141], v[32:47]
	s_waitcnt lgkmcnt(0)
	v_mfma_f32_32x32x16_bf16 v[16:31], v[134:137], v[150:153], v[16:31]
	s_and_b32 m0, s32, 7
	s_lshl_b32 m0, m0, 12
	s_add_i32 m0, m0, 0x18400
	s_nop 0
	global_load_lds_dwordx4 v[172:173], off
	v_mfma_f32_32x32x16_bf16 v[0:15], v[142:145], v[150:153], v[0:15]
	ds_read_b128 v[134:137], v83 offset:32768
	ds_read_b128 v[138:141], v82
	ds_read_b128 v[142:145], v83 offset:36864
	ds_read_b128 v[154:157], v82 offset:4096
	s_waitcnt lgkmcnt(1)
	v_mfma_f32_32x32x16_bf16 v[48:63], v[134:137], v[138:141], v[48:63]
	v_mfma_f32_32x32x16_bf16 v[32:47], v[142:145], v[138:141], v[32:47]
	s_and_b32 m0, s32, 7
	s_lshl_b32 m0, m0, 12
	s_add_i32 m0, m0, 0x18800
	s_nop 0
	global_load_lds_dwordx4 v[174:175], off
	s_waitcnt lgkmcnt(0)
	v_mfma_f32_32x32x16_bf16 v[16:31], v[134:137], v[154:157], v[16:31]
	v_mfma_f32_32x32x16_bf16 v[0:15], v[142:145], v[154:157], v[0:15]
	ds_read_b128 v[134:137], v87 offset:32768
	ds_read_b128 v[138:141], v86
	ds_read_b128 v[142:145], v87 offset:36864
	ds_read_b128 v[150:153], v86 offset:4096
	s_waitcnt lgkmcnt(1)
	v_mfma_f32_32x32x16_bf16 v[48:63], v[134:137], v[138:141], v[48:63]
	s_and_b32 m0, s32, 7
	s_lshl_b32 m0, m0, 12
	s_add_i32 m0, m0, 0x18c00
	s_nop 0
	global_load_lds_dwordx4 v[176:177], off
	v_mfma_f32_32x32x16_bf16 v[32:47], v[142:145], v[138:141], v[32:47]
	s_waitcnt lgkmcnt(0)
	v_mfma_f32_32x32x16_bf16 v[16:31], v[134:137], v[150:153], v[16:31]
	v_mfma_f32_32x32x16_bf16 v[0:15], v[142:145], v[150:153], v[0:15]
	s_and_b32 m0, s32, 7
	s_lshl_b32 m0, m0, 11
	s_add_i32 m0, m0, 0x20000
	s_nop 0
	global_load_lds_dwordx4 v[178:179], off
	ds_read_b128 v[134:137], v89 offset:32768
	ds_read_b128 v[138:141], v88
	ds_read_b128 v[142:145], v89 offset:36864
	ds_read_b128 v[154:157], v88 offset:4096
	s_waitcnt lgkmcnt(1)
	v_mfma_f32_32x32x16_bf16 v[48:63], v[134:137], v[138:141], v[48:63]
	v_mfma_f32_32x32x16_bf16 v[32:47], v[142:145], v[138:141], v[32:47]
	s_and_b32 m0, s32, 7
	s_lshl_b32 m0, m0, 11
	s_add_i32 m0, m0, 0x20400
	s_nop 0
	global_load_lds_dwordx4 v[180:181], off
	s_waitcnt vmcnt(6)
	s_waitcnt lgkmcnt(0)
	s_barrier
	s_waitcnt lgkmcnt(0)
	v_mfma_f32_32x32x16_bf16 v[16:31], v[134:137], v[154:157], v[16:31]
	v_lshl_add_u64 v[158:159], v[66:67], 0, s[30:31]
	s_nop 0
	s_nop 0
	s_nop 0
	s_nop 0
	v_lshl_add_u64 v[162:163], v[70:71], 0, s[30:31]
	s_nop 0
	v_mfma_f32_32x32x16_bf16 v[0:15], v[142:145], v[154:157], v[0:15]
	s_and_b32 m0, s32, 7
	s_lshl_b32 m0, m0, 12
	s_add_i32 m0, m0, 0x0
	s_nop 0
	global_load_lds_dwordx4 v[158:159], off
	s_nop 0
	v_lshl_add_u64 v[164:165], v[72:73], 0, s[30:31]
	s_nop 0
	s_lshr_b32 s30, s32, 15
	s_add_i32 s30, s30, 9
	s_sub_i32 s31, s30, 15
	s_cmp_ge_u32 s30, 15
	s_cselect_b32 s30, s31, s30
	s_add_i32 s30, s30, 1
	s_lshl_b32 s30, s30, 7
	s_mov_b32 s31, 0
	s_nop 0
	s_nop 0
	v_lshl_add_u64 v[174:175], v[70:71], 0, s[30:31]
	s_nop 0
	s_nop 0
	s_nop 0
	s_nop 0
	ds_read_b128 v[126:129], v91
	ds_read_b128 v[134:137], v84 offset:49152
	ds_read_b128 v[138:141], v90
	ds_read_b128 v[150:153], v84 offset:53248
	s_waitcnt lgkmcnt(1)
	v_mfma_f32_32x32x16_bf16 v[48:63], v[126:129], v[134:137], v[48:63]
	s_nop 0
	v_mfma_f32_32x32x16_bf16 v[32:47], v[138:141], v[134:137], v[32:47]
	s_waitcnt lgkmcnt(0)
	v_mfma_f32_32x32x16_bf16 v[16:31], v[126:129], v[150:153], v[16:31]
	s_and_b32 m0, s32, 7
	s_lshl_b32 m0, m0, 12
	s_add_i32 m0, m0, 0x400
	s_nop 0
	global_load_lds_dwordx4 v[160:161], off
	v_mfma_f32_32x32x16_bf16 v[0:15], v[138:141], v[150:153], v[0:15]
	ds_read_b128 v[126:129], v94
	ds_read_b128 v[134:137], v82 offset:49152
	ds_read_b128 v[138:141], v92
	ds_read_b128 v[154:157], v82 offset:53248
	s_waitcnt lgkmcnt(1)
	v_mfma_f32_32x32x16_bf16 v[48:63], v[126:129], v[134:137], v[48:63]
	v_mfma_f32_32x32x16_bf16 v[32:47], v[138:141], v[134:137], v[32:47]
	s_and_b32 m0, s32, 7
	s_lshl_b32 m0, m0, 12
	s_add_i32 m0, m0, 0x800
	s_nop 0
	global_load_lds_dwordx4 v[162:163], off
	s_waitcnt lgkmcnt(0)
	v_mfma_f32_32x32x16_bf16 v[16:31], v[126:129], v[154:157], v[16:31]
	v_mfma_f32_32x32x16_bf16 v[0:15], v[138:141], v[154:157], v[0:15]
	ds_read_b128 v[126:129], v95
	ds_read_b128 v[134:137], v86 offset:49152
	ds_read_b128 v[138:141], v93
	ds_read_b128 v[150:153], v86 offset:53248
	s_waitcnt lgkmcnt(1)
	v_mfma_f32_32x32x16_bf16 v[48:63], v[126:129], v[134:137], v[48:63]
	s_and_b32 m0, s32, 7
	s_lshl_b32 m0, m0, 12
	s_add_i32 m0, m0, 0xc00
	s_nop 0
	global_load_lds_dwordx4 v[164:165], off
	v_mfma_f32_32x32x16_bf16 v[32:47], v[138:141], v[134:137], v[32:47]
	s_waitcnt lgkmcnt(0)
	v_mfma_f32_32x32x16_bf16 v[16:31], v[126:129], v[150:153], v[16:31]
	v_mfma_f32_32x32x16_bf16 v[0:15], v[138:141], v[150:153], v[0:15]
	s_and_b32 m0, s32, 7
	s_lshl_b32 m0, m0, 11
	s_add_i32 m0, m0, 0x8000
	s_nop 0
	global_load_lds_dwordx4 v[166:167], off
	ds_read_b128 v[126:129], v97
	ds_read_b128 v[134:137], v88 offset:49152
	ds_read_b128 v[138:141], v96
	ds_read_b128 v[154:157], v88 offset:53248
	s_waitcnt lgkmcnt(1)
	v_mfma_f32_32x32x16_bf16 v[48:63], v[126:129], v[134:137], v[48:63]
	v_mfma_f32_32x32x16_bf16 v[32:47], v[138:141], v[134:137], v[32:47]
	s_and_b32 m0, s32, 7
	s_lshl_b32 m0, m0, 11
	s_add_i32 m0, m0, 0x8400
	s_nop 0
	global_load_lds_dwordx4 v[168:169], off
	s_waitcnt vmcnt(6)
	s_waitcnt lgkmcnt(0)
	s_barrier
	s_waitcnt lgkmcnt(0)
	v_mfma_f32_32x32x16_bf16 v[16:31], v[126:129], v[154:157], v[16:31]
	v_lshl_add_u64 v[170:171], v[66:67], 0, s[30:31]
	s_nop 0
	v_lshl_add_u64 v[172:173], v[68:69], 0, s[30:31]
	s_nop 0
	s_nop 0
	s_nop 0
	s_nop 0
	v_mfma_f32_32x32x16_bf16 v[0:15], v[138:141], v[154:157], v[0:15]
	s_and_b32 m0, s32, 7
	s_lshl_b32 m0, m0, 12
	s_add_i32 m0, m0, 0xc000
	s_nop 0
	global_load_lds_dwordx4 v[170:171], off
	s_nop 0
	v_lshl_add_u64 v[176:177], v[72:73], 0, s[30:31]
	s_nop 0
	s_nop 0
	s_nop 0
	v_lshl_add_u64 v[178:179], v[74:75], 0, s[30:31]
	s_nop 0
	s_nop 0
	s_nop 0
	v_lshl_add_u64 v[180:181], v[76:77], 0, s[30:31]
	s_nop 0
	s_lshr_b32 s30, s32, 15
	s_add_i32 s30, s30, 10
	s_sub_i32 s31, s30, 15
	s_cmp_ge_u32 s30, 15
	s_cselect_b32 s30, s31, s30
	s_add_i32 s30, s30, 1
	s_lshl_b32 s30, s30, 7
	s_mov_b32 s31, 0
	s_nop 0
	ds_read_b128 v[120:123], v98
	ds_read_b128 v[124:127], v100
	ds_read_b128 v[128:131], v99
	ds_read_b128 v[150:153], v101
	s_waitcnt lgkmcnt(1)
	v_mfma_f32_32x32x16_bf16 v[48:63], v[120:123], v[124:127], v[48:63]
	s_nop 0
	v_lshl_add_u64 v[162:163], v[70:71], 0, s[30:31]
	v_mfma_f32_32x32x16_bf16 v[32:47], v[128:131], v[124:127], v[32:47]
	s_waitcnt lgkmcnt(0)
	v_mfma_f32_32x32x16_bf16 v[16:31], v[120:123], v[150:153], v[16:31]
	s_and_b32 m0, s32, 7
	s_lshl_b32 m0, m0, 12
	s_add_i32 m0, m0, 0xc400
	s_nop 0
	global_load_lds_dwordx4 v[172:173], off
	v_mfma_f32_32x32x16_bf16 v[0:15], v[128:131], v[150:153], v[0:15]
	ds_read_b128 v[120:123], v103
	ds_read_b128 v[124:127], v104
	ds_read_b128 v[128:131], v102
	ds_read_b128 v[154:157], v105
	s_waitcnt lgkmcnt(1)
	v_mfma_f32_32x32x16_bf16 v[48:63], v[120:123], v[124:127], v[48:63]
	v_mfma_f32_32x32x16_bf16 v[32:47], v[128:131], v[124:127], v[32:47]
	s_and_b32 m0, s32, 7
	s_lshl_b32 m0, m0, 12
	s_add_i32 m0, m0, 0xc800
	s_nop 0
	global_load_lds_dwordx4 v[174:175], off
	s_waitcnt lgkmcnt(0)
	v_mfma_f32_32x32x16_bf16 v[16:31], v[120:123], v[154:157], v[16:31]
	v_mfma_f32_32x32x16_bf16 v[0:15], v[128:131], v[154:157], v[0:15]
	ds_read_b128 v[120:123], v107
	ds_read_b128 v[124:127], v108
	ds_read_b128 v[128:131], v106
	ds_read_b128 v[150:153], v109
	s_waitcnt lgkmcnt(1)
	v_mfma_f32_32x32x16_bf16 v[48:63], v[120:123], v[124:127], v[48:63]
	s_and_b32 m0, s32, 7
	s_lshl_b32 m0, m0, 12
	s_add_i32 m0, m0, 0xcc00
	s_nop 0
	global_load_lds_dwordx4 v[176:177], off
	v_mfma_f32_32x32x16_bf16 v[32:47], v[128:131], v[124:127], v[32:47]
	s_waitcnt lgkmcnt(0)
	v_mfma_f32_32x32x16_bf16 v[16:31], v[120:123], v[150:153], v[16:31]
	v_mfma_f32_32x32x16_bf16 v[0:15], v[128:131], v[150:153], v[0:15]
	s_and_b32 m0, s32, 7
	s_lshl_b32 m0, m0, 11
	s_add_i32 m0, m0, 0x14000
	s_nop 0
	global_load_lds_dwordx4 v[178:179], off
	ds_read_b128 v[120:123], v111
	ds_read_b128 v[124:127], v112
	ds_read_b128 v[128:131], v110
	ds_read_b128 v[154:157], v113
	s_waitcnt lgkmcnt(1)
	v_mfma_f32_32x32x16_bf16 v[48:63], v[120:123], v[124:127], v[48:63]
	v_mfma_f32_32x32x16_bf16 v[32:47], v[128:131], v[124:127], v[32:47]
	s_and_b32 m0, s32, 7
	s_lshl_b32 m0, m0, 11
	s_add_i32 m0, m0, 0x14400
	s_nop 0
	global_load_lds_dwordx4 v[180:181], off
	s_waitcnt vmcnt(6)
	s_waitcnt lgkmcnt(0)
	s_barrier
	s_waitcnt lgkmcnt(0)
	v_mfma_f32_32x32x16_bf16 v[16:31], v[120:123], v[154:157], v[16:31]
	v_lshl_add_u64 v[158:159], v[66:67], 0, s[30:31]
	s_nop 0
	v_lshl_add_u64 v[160:161], v[68:69], 0, s[30:31]
	s_nop 0
	s_nop 0
	s_nop 0
	s_nop 0
	v_mfma_f32_32x32x16_bf16 v[0:15], v[128:131], v[154:157], v[0:15]
	s_and_b32 m0, s32, 7
	s_lshl_b32 m0, m0, 12
	s_add_i32 m0, m0, 0x18000
	s_nop 0
	global_load_lds_dwordx4 v[158:159], off
	s_nop 0
	v_lshl_add_u64 v[164:165], v[72:73], 0, s[30:31]
	s_nop 0
	s_nop 0
	s_nop 0
	v_lshl_add_u64 v[166:167], v[74:75], 0, s[30:31]
	s_nop 0
	s_nop 0
	s_nop 0
	v_lshl_add_u64 v[168:169], v[76:77], 0, s[30:31]
	s_nop 0
	s_lshr_b32 s30, s32, 15
	s_add_i32 s30, s30, 11
	s_sub_i32 s31, s30, 15
	s_cmp_ge_u32 s30, 15
	s_cselect_b32 s30, s31, s30
	s_add_i32 s30, s30, 1
	s_lshl_b32 s30, s30, 7
	s_mov_b32 s31, 0
	s_nop 0
	ds_read_b128 v[114:117], v85 offset:32768
	ds_read_b128 v[118:121], v84
	ds_read_b128 v[122:125], v85 offset:36864
	ds_read_b128 v[150:153], v84 offset:4096
	s_waitcnt lgkmcnt(1)
	v_mfma_f32_32x32x16_bf16 v[48:63], v[114:117], v[118:121], v[48:63]
	s_nop 0
	v_mfma_f32_32x32x16_bf16 v[32:47], v[122:125], v[118:121], v[32:47]
	s_waitcnt lgkmcnt(0)
	v_mfma_f32_32x32x16_bf16 v[16:31], v[114:117], v[150:153], v[16:31]
	s_and_b32 m0, s32, 7
	s_lshl_b32 m0, m0, 12
	s_add_i32 m0, m0, 0x18400
	s_nop 0
	global_load_lds_dwordx4 v[160:161], off
	v_mfma_f32_32x32x16_bf16 v[0:15], v[122:125], v[150:153], v[0:15]
	ds_read_b128 v[114:117], v83 offset:32768
	ds_read_b128 v[118:121], v82
	ds_read_b128 v[122:125], v83 offset:36864
	ds_read_b128 v[154:157], v82 offset:4096
	s_waitcnt lgkmcnt(1)
	v_mfma_f32_32x32x16_bf16 v[48:63], v[114:117], v[118:121], v[48:63]
	v_mfma_f32_32x32x16_bf16 v[32:47], v[122:125], v[118:121], v[32:47]
	s_and_b32 m0, s32, 7
	s_lshl_b32 m0, m0, 12
	s_add_i32 m0, m0, 0x18800
	s_nop 0
	global_load_lds_dwordx4 v[162:163], off
	s_waitcnt lgkmcnt(0)
	v_mfma_f32_32x32x16_bf16 v[16:31], v[114:117], v[154:157], v[16:31]
	v_mfma_f32_32x32x16_bf16 v[0:15], v[122:125], v[154:157], v[0:15]
	ds_read_b128 v[114:117], v87 offset:32768
	ds_read_b128 v[118:121], v86
	ds_read_b128 v[122:125], v87 offset:36864
	ds_read_b128 v[150:153], v86 offset:4096
	s_waitcnt lgkmcnt(1)
	v_mfma_f32_32x32x16_bf16 v[48:63], v[114:117], v[118:121], v[48:63]
	s_and_b32 m0, s32, 7
	s_lshl_b32 m0, m0, 12
	s_add_i32 m0, m0, 0x18c00
	s_nop 0
	global_load_lds_dwordx4 v[164:165], off
	v_mfma_f32_32x32x16_bf16 v[32:47], v[122:125], v[118:121], v[32:47]
	s_waitcnt lgkmcnt(0)
	v_mfma_f32_32x32x16_bf16 v[16:31], v[114:117], v[150:153], v[16:31]
	v_mfma_f32_32x32x16_bf16 v[0:15], v[122:125], v[150:153], v[0:15]
	s_and_b32 m0, s32, 7
	s_lshl_b32 m0, m0, 11
	s_add_i32 m0, m0, 0x20000
	s_nop 0
	global_load_lds_dwordx4 v[166:167], off
	ds_read_b128 v[114:117], v89 offset:32768
	ds_read_b128 v[118:121], v88
	ds_read_b128 v[122:125], v89 offset:36864
	ds_read_b128 v[154:157], v88 offset:4096
	s_waitcnt lgkmcnt(1)
	v_mfma_f32_32x32x16_bf16 v[48:63], v[114:117], v[118:121], v[48:63]
	v_mfma_f32_32x32x16_bf16 v[32:47], v[122:125], v[118:121], v[32:47]
	s_and_b32 m0, s32, 7
	s_lshl_b32 m0, m0, 11
	s_add_i32 m0, m0, 0x20400
	s_nop 0
	global_load_lds_dwordx4 v[168:169], off
	s_waitcnt vmcnt(6)
	s_waitcnt lgkmcnt(0)
	s_barrier
	s_waitcnt lgkmcnt(0)
	v_mfma_f32_32x32x16_bf16 v[16:31], v[114:117], v[154:157], v[16:31]
	v_lshl_add_u64 v[170:171], v[66:67], 0, s[30:31]
	s_nop 0
	v_lshl_add_u64 v[172:173], v[68:69], 0, s[30:31]
	s_nop 0
	s_nop 0
	s_nop 0
	v_lshl_add_u64 v[174:175], v[70:71], 0, s[30:31]
	s_nop 0
	v_mfma_f32_32x32x16_bf16 v[0:15], v[122:125], v[154:157], v[0:15]
	s_and_b32 m0, s32, 7
	s_lshl_b32 m0, m0, 12
	s_add_i32 m0, m0, 0x0
	s_nop 0
	global_load_lds_dwordx4 v[170:171], off
	s_nop 0
	v_lshl_add_u64 v[176:177], v[72:73], 0, s[30:31]
	s_nop 0
	s_nop 0
	s_nop 0
	v_lshl_add_u64 v[178:179], v[74:75], 0, s[30:31]
	s_nop 0
	s_nop 0
	s_nop 0
	v_lshl_add_u64 v[180:181], v[76:77], 0, s[30:31]
	s_nop 0
	s_lshr_b32 s30, s32, 15
	s_add_i32 s30, s30, 12
	s_sub_i32 s31, s30, 15
	s_cmp_ge_u32 s30, 15
	s_cselect_b32 s30, s31, s30
	s_add_i32 s30, s30, 1
	s_lshl_b32 s30, s30, 7
	s_mov_b32 s31, 0
	s_nop 0
	ds_read_b128 v[114:117], v91
	ds_read_b128 v[118:121], v84 offset:49152
	ds_read_b128 v[122:125], v90
	ds_read_b128 v[150:153], v84 offset:53248
	s_waitcnt lgkmcnt(1)
	v_mfma_f32_32x32x16_bf16 v[48:63], v[114:117], v[118:121], v[48:63]
	s_nop 0
	v_mfma_f32_32x32x16_bf16 v[32:47], v[122:125], v[118:121], v[32:47]
	s_waitcnt lgkmcnt(0)
	v_mfma_f32_32x32x16_bf16 v[16:31], v[114:117], v[150:153], v[16:31]
	s_and_b32 m0, s32, 7
	s_lshl_b32 m0, m0, 12
	s_add_i32 m0, m0, 0x400
	s_nop 0
	global_load_lds_dwordx4 v[172:173], off
	v_mfma_f32_32x32x16_bf16 v[0:15], v[122:125], v[150:153], v[0:15]
	ds_read_b128 v[114:117], v94
	ds_read_b128 v[118:121], v82 offset:49152
	ds_read_b128 v[122:125], v92
	ds_read_b128 v[154:157], v82 offset:53248
	s_waitcnt lgkmcnt(1)
	v_mfma_f32_32x32x16_bf16 v[48:63], v[114:117], v[118:121], v[48:63]
	v_mfma_f32_32x32x16_bf16 v[32:47], v[122:125], v[118:121], v[32:47]
	s_and_b32 m0, s32, 7
	s_lshl_b32 m0, m0, 12
	s_add_i32 m0, m0, 0x800
	s_nop 0
	global_load_lds_dwordx4 v[174:175], off
	s_waitcnt lgkmcnt(0)
	v_mfma_f32_32x32x16_bf16 v[16:31], v[114:117], v[154:157], v[16:31]
	v_mfma_f32_32x32x16_bf16 v[0:15], v[122:125], v[154:157], v[0:15]
	ds_read_b128 v[114:117], v95
	ds_read_b128 v[118:121], v86 offset:49152
	ds_read_b128 v[122:125], v93
	ds_read_b128 v[150:153], v86 offset:53248
	s_waitcnt lgkmcnt(1)
	v_mfma_f32_32x32x16_bf16 v[48:63], v[114:117], v[118:121], v[48:63]
	s_and_b32 m0, s32, 7
	s_lshl_b32 m0, m0, 12
	s_add_i32 m0, m0, 0xc00
	s_nop 0
	global_load_lds_dwordx4 v[176:177], off
	v_mfma_f32_32x32x16_bf16 v[32:47], v[122:125], v[118:121], v[32:47]
	s_waitcnt lgkmcnt(0)
	v_mfma_f32_32x32x16_bf16 v[16:31], v[114:117], v[150:153], v[16:31]
	v_mfma_f32_32x32x16_bf16 v[0:15], v[122:125], v[150:153], v[0:15]
	s_and_b32 m0, s32, 7
	s_lshl_b32 m0, m0, 11
	s_add_i32 m0, m0, 0x8000
	s_nop 0
	global_load_lds_dwordx4 v[178:179], off
	ds_read_b128 v[114:117], v97
	ds_read_b128 v[118:121], v88 offset:49152
	ds_read_b128 v[122:125], v96
	ds_read_b128 v[154:157], v88 offset:53248
	s_waitcnt lgkmcnt(1)
	v_mfma_f32_32x32x16_bf16 v[48:63], v[114:117], v[118:121], v[48:63]
	v_mfma_f32_32x32x16_bf16 v[32:47], v[122:125], v[118:121], v[32:47]
	s_and_b32 m0, s32, 7
	s_lshl_b32 m0, m0, 11
	s_add_i32 m0, m0, 0x8400
	s_nop 0
	global_load_lds_dwordx4 v[180:181], off
	s_waitcnt vmcnt(6)
	s_waitcnt lgkmcnt(0)
	s_barrier
	s_waitcnt lgkmcnt(0)
	v_mfma_f32_32x32x16_bf16 v[16:31], v[114:117], v[154:157], v[16:31]
	v_lshl_add_u64 v[158:159], v[66:67], 0, s[30:31]
	s_nop 0
	v_lshl_add_u64 v[160:161], v[68:69], 0, s[30:31]
	s_nop 0
	s_nop 0
	s_nop 0
	v_lshl_add_u64 v[162:163], v[70:71], 0, s[30:31]
	s_nop 0
	v_mfma_f32_32x32x16_bf16 v[0:15], v[122:125], v[154:157], v[0:15]
	s_and_b32 m0, s32, 7
	s_lshl_b32 m0, m0, 12
	s_add_i32 m0, m0, 0xc000
	s_nop 0
	global_load_lds_dwordx4 v[158:159], off
	s_nop 0
	v_lshl_add_u64 v[164:165], v[72:73], 0, s[30:31]
	s_nop 0
	s_nop 0
	s_nop 0
	v_lshl_add_u64 v[166:167], v[74:75], 0, s[30:31]
	s_nop 0
	s_nop 0
	s_nop 0
	v_lshl_add_u64 v[168:169], v[76:77], 0, s[30:31]
	s_nop 0
	s_lshr_b32 s30, s32, 15
	s_add_i32 s30, s30, 13
	s_sub_i32 s31, s30, 15
	s_cmp_ge_u32 s30, 15
	s_cselect_b32 s30, s31, s30
	s_add_i32 s30, s30, 1
	s_lshl_b32 s30, s30, 7
	s_mov_b32 s31, 0
	s_nop 0
	ds_read_b128 v[114:117], v98
	ds_read_b128 v[118:121], v100
	ds_read_b128 v[122:125], v99
	ds_read_b128 v[150:153], v101
	s_waitcnt lgkmcnt(1)
	v_mfma_f32_32x32x16_bf16 v[48:63], v[114:117], v[118:121], v[48:63]
	s_nop 0
	v_mfma_f32_32x32x16_bf16 v[32:47], v[122:125], v[118:121], v[32:47]
	s_waitcnt lgkmcnt(0)
	v_mfma_f32_32x32x16_bf16 v[16:31], v[114:117], v[150:153], v[16:31]
	s_and_b32 m0, s32, 7
	s_lshl_b32 m0, m0, 12
	s_add_i32 m0, m0, 0xc400
	s_nop 0
	global_load_lds_dwordx4 v[160:161], off
	v_mfma_f32_32x32x16_bf16 v[0:15], v[122:125], v[150:153], v[0:15]
	ds_read_b128 v[114:117], v103
	ds_read_b128 v[118:121], v104
	ds_read_b128 v[122:125], v102
	ds_read_b128 v[154:157], v105
	s_waitcnt lgkmcnt(1)
	v_mfma_f32_32x32x16_bf16 v[48:63], v[114:117], v[118:121], v[48:63]
	v_mfma_f32_32x32x16_bf16 v[32:47], v[122:125], v[118:121], v[32:47]
	s_and_b32 m0, s32, 7
	s_lshl_b32 m0, m0, 12
	s_add_i32 m0, m0, 0xc800
	s_nop 0
	global_load_lds_dwordx4 v[162:163], off
	s_waitcnt lgkmcnt(0)
	v_mfma_f32_32x32x16_bf16 v[16:31], v[114:117], v[154:157], v[16:31]
	v_mfma_f32_32x32x16_bf16 v[0:15], v[122:125], v[154:157], v[0:15]
	ds_read_b128 v[114:117], v107
	ds_read_b128 v[118:121], v108
	ds_read_b128 v[122:125], v106
	ds_read_b128 v[150:153], v109
	s_waitcnt lgkmcnt(1)
	v_mfma_f32_32x32x16_bf16 v[48:63], v[114:117], v[118:121], v[48:63]
	s_and_b32 m0, s32, 7
	s_lshl_b32 m0, m0, 12
	s_add_i32 m0, m0, 0xcc00
	s_nop 0
	global_load_lds_dwordx4 v[164:165], off
	v_mfma_f32_32x32x16_bf16 v[32:47], v[122:125], v[118:121], v[32:47]
	s_waitcnt lgkmcnt(0)
	v_mfma_f32_32x32x16_bf16 v[16:31], v[114:117], v[150:153], v[16:31]
	v_mfma_f32_32x32x16_bf16 v[0:15], v[122:125], v[150:153], v[0:15]
	s_and_b32 m0, s32, 7
	s_lshl_b32 m0, m0, 11
	s_add_i32 m0, m0, 0x14000
	s_nop 0
	global_load_lds_dwordx4 v[166:167], off
	ds_read_b128 v[114:117], v111
	ds_read_b128 v[118:121], v112
	ds_read_b128 v[122:125], v110
	ds_read_b128 v[154:157], v113
	s_waitcnt lgkmcnt(1)
	v_mfma_f32_32x32x16_bf16 v[48:63], v[114:117], v[118:121], v[48:63]
	v_mfma_f32_32x32x16_bf16 v[32:47], v[122:125], v[118:121], v[32:47]
	s_and_b32 m0, s32, 7
	s_lshl_b32 m0, m0, 11
	s_add_i32 m0, m0, 0x14400
	s_nop 0
	global_load_lds_dwordx4 v[168:169], off
	s_waitcnt vmcnt(6)
	s_waitcnt lgkmcnt(0)
	s_barrier
	s_waitcnt lgkmcnt(0)
	v_mfma_f32_32x32x16_bf16 v[16:31], v[114:117], v[154:157], v[16:31]
	v_lshl_add_u64 v[170:171], v[66:67], 0, s[30:31]
	s_nop 0
	v_lshl_add_u64 v[172:173], v[68:69], 0, s[30:31]
	s_nop 0
	s_nop 0
	s_nop 0
	v_lshl_add_u64 v[174:175], v[70:71], 0, s[30:31]
	s_nop 0
	v_mfma_f32_32x32x16_bf16 v[0:15], v[122:125], v[154:157], v[0:15]
	s_and_b32 m0, s32, 7
	s_lshl_b32 m0, m0, 12
	s_add_i32 m0, m0, 0x18000
	s_nop 0
	global_load_lds_dwordx4 v[170:171], off
	s_nop 0
	v_lshl_add_u64 v[176:177], v[72:73], 0, s[30:31]
	s_nop 0
	s_nop 0
	s_nop 0
	v_lshl_add_u64 v[178:179], v[74:75], 0, s[30:31]
	s_nop 0
	s_nop 0
	s_nop 0
	v_lshl_add_u64 v[180:181], v[76:77], 0, s[30:31]
	s_nop 0
	s_lshr_b32 s30, s32, 15
	s_add_i32 s30, s30, 14
	s_sub_i32 s31, s30, 15
	s_cmp_ge_u32 s30, 15
	s_cselect_b32 s30, s31, s30
	s_add_i32 s30, s30, 1
	s_lshl_b32 s30, s30, 7
	s_mov_b32 s31, 0
	s_nop 0
	ds_read_b128 v[114:117], v85 offset:32768
	ds_read_b128 v[118:121], v84
	ds_read_b128 v[122:125], v85 offset:36864
	ds_read_b128 v[150:153], v84 offset:4096
	s_waitcnt lgkmcnt(1)
	v_mfma_f32_32x32x16_bf16 v[48:63], v[114:117], v[118:121], v[48:63]
	v_lshl_add_u64 v[158:159], v[66:67], 0, s[30:31]
	s_nop 0
	v_mfma_f32_32x32x16_bf16 v[32:47], v[122:125], v[118:121], v[32:47]
	s_waitcnt lgkmcnt(0)
	v_mfma_f32_32x32x16_bf16 v[16:31], v[114:117], v[150:153], v[16:31]
	s_and_b32 m0, s32, 7
	s_lshl_b32 m0, m0, 12
	s_add_i32 m0, m0, 0x18400
	s_nop 0
	global_load_lds_dwordx4 v[172:173], off
	v_mfma_f32_32x32x16_bf16 v[0:15], v[122:125], v[150:153], v[0:15]
	ds_read_b128 v[114:117], v83 offset:32768
	ds_read_b128 v[118:121], v82
	ds_read_b128 v[122:125], v83 offset:36864
	ds_read_b128 v[154:157], v82 offset:4096
	s_waitcnt lgkmcnt(1)
	v_mfma_f32_32x32x16_bf16 v[48:63], v[114:117], v[118:121], v[48:63]
	v_mfma_f32_32x32x16_bf16 v[32:47], v[122:125], v[118:121], v[32:47]
	s_and_b32 m0, s32, 7
	s_lshl_b32 m0, m0, 12
	s_add_i32 m0, m0, 0x18800
	s_nop 0
	global_load_lds_dwordx4 v[174:175], off
	s_waitcnt lgkmcnt(0)
	v_mfma_f32_32x32x16_bf16 v[16:31], v[114:117], v[154:157], v[16:31]
	v_mfma_f32_32x32x16_bf16 v[0:15], v[122:125], v[154:157], v[0:15]
	ds_read_b128 v[114:117], v87 offset:32768
	ds_read_b128 v[118:121], v86
	ds_read_b128 v[122:125], v87 offset:36864
	ds_read_b128 v[150:153], v86 offset:4096
	s_waitcnt lgkmcnt(1)
	v_mfma_f32_32x32x16_bf16 v[48:63], v[114:117], v[118:121], v[48:63]
	s_and_b32 m0, s32, 7
	s_lshl_b32 m0, m0, 12
	s_add_i32 m0, m0, 0x18c00
	s_nop 0
	global_load_lds_dwordx4 v[176:177], off
	v_mfma_f32_32x32x16_bf16 v[32:47], v[122:125], v[118:121], v[32:47]
	s_waitcnt lgkmcnt(0)
	v_mfma_f32_32x32x16_bf16 v[16:31], v[114:117], v[150:153], v[16:31]
	v_mfma_f32_32x32x16_bf16 v[0:15], v[122:125], v[150:153], v[0:15]
	s_and_b32 m0, s32, 7
	s_lshl_b32 m0, m0, 11
	s_add_i32 m0, m0, 0x20000
	s_nop 0
	global_load_lds_dwordx4 v[178:179], off
	ds_read_b128 v[114:117], v89 offset:32768
	ds_read_b128 v[118:121], v88
	ds_read_b128 v[122:125], v89 offset:36864
	ds_read_b128 v[154:157], v88 offset:4096
	s_waitcnt lgkmcnt(1)
	v_mfma_f32_32x32x16_bf16 v[48:63], v[114:117], v[118:121], v[48:63]
	v_mfma_f32_32x32x16_bf16 v[32:47], v[122:125], v[118:121], v[32:47]
	s_and_b32 m0, s32, 7
	s_lshl_b32 m0, m0, 11
	s_add_i32 m0, m0, 0x20400
	s_nop 0
	global_load_lds_dwordx4 v[180:181], off
	s_waitcnt vmcnt(6)
	s_waitcnt lgkmcnt(0)
	s_barrier
	s_nop 0
	v_lshl_add_u64 v[160:161], v[68:69], 0, s[30:31]
	s_nop 0
	s_waitcnt lgkmcnt(0)
	v_mfma_f32_32x32x16_bf16 v[16:31], v[114:117], v[154:157], v[16:31]
	s_nop 0
	v_lshl_add_u64 v[162:163], v[70:71], 0, s[30:31]
	s_nop 0
	s_nop 0
	s_nop 0
	v_lshl_add_u64 v[164:165], v[72:73], 0, s[30:31]
	s_nop 0
	v_mfma_f32_32x32x16_bf16 v[0:15], v[122:125], v[154:157], v[0:15]
	s_and_b32 m0, s32, 7
	s_lshl_b32 m0, m0, 12
	s_add_i32 m0, m0, 0x0
	s_nop 0
	global_load_lds_dwordx4 v[158:159], off
	s_nop 0
	v_lshl_add_u64 v[166:167], v[74:75], 0, s[30:31]
	s_nop 0
	s_nop 0
	s_nop 0
	v_lshl_add_u64 v[168:169], v[76:77], 0, s[30:31]
	s_nop 0
	s_nop 0
	s_nop 0
	ds_read_b128 v[66:69], v91
	ds_read_b128 v[70:73], v84 offset:49152
	ds_read_b128 v[74:77], v90
	ds_read_b128 v[150:153], v84 offset:53248
	s_waitcnt lgkmcnt(1)
	v_mfma_f32_32x32x16_bf16 v[48:63], v[66:69], v[70:73], v[48:63]
	v_mfma_f32_32x32x16_bf16 v[32:47], v[74:77], v[70:73], v[32:47]
	s_waitcnt lgkmcnt(0)
	v_mfma_f32_32x32x16_bf16 v[16:31], v[66:69], v[150:153], v[16:31]
	s_and_b32 m0, s32, 7
	s_lshl_b32 m0, m0, 12
	s_add_i32 m0, m0, 0x400
	s_nop 0
	global_load_lds_dwordx4 v[160:161], off
	v_mfma_f32_32x32x16_bf16 v[0:15], v[74:77], v[150:153], v[0:15]
	ds_read_b128 v[66:69], v94
	ds_read_b128 v[70:73], v82 offset:49152
	ds_read_b128 v[74:77], v92
	ds_read_b128 v[154:157], v82 offset:53248
	s_waitcnt lgkmcnt(1)
	v_mfma_f32_32x32x16_bf16 v[48:63], v[66:69], v[70:73], v[48:63]
	v_mfma_f32_32x32x16_bf16 v[32:47], v[74:77], v[70:73], v[32:47]
	s_and_b32 m0, s32, 7
	s_lshl_b32 m0, m0, 12
	s_add_i32 m0, m0, 0x800
	s_nop 0
	global_load_lds_dwordx4 v[162:163], off
	s_waitcnt lgkmcnt(0)
	v_mfma_f32_32x32x16_bf16 v[16:31], v[66:69], v[154:157], v[16:31]
	v_mfma_f32_32x32x16_bf16 v[0:15], v[74:77], v[154:157], v[0:15]
	ds_read_b128 v[66:69], v95
	ds_read_b128 v[70:73], v86 offset:49152
	ds_read_b128 v[74:77], v93
	ds_read_b128 v[150:153], v86 offset:53248
	s_waitcnt lgkmcnt(1)
	v_mfma_f32_32x32x16_bf16 v[48:63], v[66:69], v[70:73], v[48:63]
	s_and_b32 m0, s32, 7
	s_lshl_b32 m0, m0, 12
	s_add_i32 m0, m0, 0xc00
	s_nop 0
	global_load_lds_dwordx4 v[164:165], off
	v_mfma_f32_32x32x16_bf16 v[32:47], v[74:77], v[70:73], v[32:47]
	s_waitcnt lgkmcnt(0)
	v_mfma_f32_32x32x16_bf16 v[16:31], v[66:69], v[150:153], v[16:31]
	v_mfma_f32_32x32x16_bf16 v[0:15], v[74:77], v[150:153], v[0:15]
	s_and_b32 m0, s32, 7
	s_lshl_b32 m0, m0, 11
	s_add_i32 m0, m0, 0x8000
	s_nop 0
	global_load_lds_dwordx4 v[166:167], off
	ds_read_b128 v[66:69], v97
	ds_read_b128 v[70:73], v88 offset:49152
	ds_read_b128 v[74:77], v96
	ds_read_b128 v[154:157], v88 offset:53248
	s_waitcnt lgkmcnt(1)
	v_mfma_f32_32x32x16_bf16 v[48:63], v[66:69], v[70:73], v[48:63]
	v_mfma_f32_32x32x16_bf16 v[32:47], v[74:77], v[70:73], v[32:47]
	s_and_b32 m0, s32, 7
	s_lshl_b32 m0, m0, 11
	s_add_i32 m0, m0, 0x8400
	s_nop 0
	global_load_lds_dwordx4 v[168:169], off
	s_waitcnt vmcnt(6)
	s_waitcnt lgkmcnt(0)
	s_barrier
	s_waitcnt lgkmcnt(0)
	v_mfma_f32_32x32x16_bf16 v[16:31], v[66:69], v[154:157], v[16:31]
	v_lshrrev_b32_e32 v183, 7, v133
	v_and_b32_e32 v184, 31, v133
	v_lshl_or_b32 v183, v183, 6, v184
	v_add_u32_e32 v183, s2, v183
	v_lshlrev_b32_e32 v183, 2, v183
	global_load_dword v184, v183, s[76:77]
	global_load_dword v185, v183, s[76:77] offset:128
	v_mfma_f32_32x32x16_bf16 v[0:15], v[74:77], v[154:157], v[0:15]
	ds_read_b128 v[66:69], v98
	ds_read_b128 v[70:73], v100
	ds_read_b128 v[74:77], v99
	ds_read_b128 v[150:153], v101
	s_waitcnt lgkmcnt(1)
	v_mfma_f32_32x32x16_bf16 v[48:63], v[66:69], v[70:73], v[48:63]
	v_mfma_f32_32x32x16_bf16 v[32:47], v[74:77], v[70:73], v[32:47]
	s_waitcnt lgkmcnt(0)
	v_mfma_f32_32x32x16_bf16 v[16:31], v[66:69], v[150:153], v[16:31]
	v_mfma_f32_32x32x16_bf16 v[0:15], v[74:77], v[150:153], v[0:15]
	ds_read_b128 v[66:69], v103
	ds_read_b128 v[70:73], v104
	ds_read_b128 v[74:77], v102
	ds_read_b128 v[154:157], v105
	s_waitcnt lgkmcnt(1)
	v_mfma_f32_32x32x16_bf16 v[48:63], v[66:69], v[70:73], v[48:63]
	v_mfma_f32_32x32x16_bf16 v[32:47], v[74:77], v[70:73], v[32:47]
	s_waitcnt lgkmcnt(0)
	v_mfma_f32_32x32x16_bf16 v[16:31], v[66:69], v[154:157], v[16:31]
	v_mfma_f32_32x32x16_bf16 v[0:15], v[74:77], v[154:157], v[0:15]
	ds_read_b128 v[66:69], v107
	ds_read_b128 v[70:73], v108
	ds_read_b128 v[74:77], v106
	ds_read_b128 v[150:153], v109
	s_waitcnt lgkmcnt(1)
	v_mfma_f32_32x32x16_bf16 v[48:63], v[66:69], v[70:73], v[48:63]
	v_mfma_f32_32x32x16_bf16 v[32:47], v[74:77], v[70:73], v[32:47]
	s_waitcnt lgkmcnt(0)
	v_mfma_f32_32x32x16_bf16 v[16:31], v[66:69], v[150:153], v[16:31]
	v_mfma_f32_32x32x16_bf16 v[0:15], v[74:77], v[150:153], v[0:15]
	ds_read_b128 v[66:69], v111
	ds_read_b128 v[70:73], v112
	ds_read_b128 v[74:77], v110
	ds_read_b128 v[154:157], v113
	s_waitcnt lgkmcnt(1)
	v_mfma_f32_32x32x16_bf16 v[48:63], v[66:69], v[70:73], v[48:63]
	v_mfma_f32_32x32x16_bf16 v[32:47], v[74:77], v[70:73], v[32:47]
	s_waitcnt vmcnt(0)
	s_waitcnt lgkmcnt(0)
	s_barrier
	s_waitcnt lgkmcnt(0)
	v_mfma_f32_32x32x16_bf16 v[16:31], v[66:69], v[154:157], v[16:31]
	v_mfma_f32_32x32x16_bf16 v[0:15], v[74:77], v[154:157], v[0:15]
	ds_read_b128 v[66:69], v85 offset:32768
	ds_read_b128 v[70:73], v84
	ds_read_b128 v[74:77], v85 offset:36864
	ds_read_b128 v[150:153], v84 offset:4096
	s_waitcnt lgkmcnt(1)
	v_mfma_f32_32x32x16_bf16 v[48:63], v[66:69], v[70:73], v[48:63]
	v_mfma_f32_32x32x16_bf16 v[32:47], v[74:77], v[70:73], v[32:47]
	s_waitcnt lgkmcnt(0)
	v_mfma_f32_32x32x16_bf16 v[16:31], v[66:69], v[150:153], v[16:31]
	v_mfma_f32_32x32x16_bf16 v[0:15], v[74:77], v[150:153], v[0:15]
	ds_read_b128 v[66:69], v83 offset:32768
	ds_read_b128 v[70:73], v82
	ds_read_b128 v[74:77], v83 offset:36864
	ds_read_b128 v[154:157], v82 offset:4096
	s_waitcnt lgkmcnt(1)
	v_mfma_f32_32x32x16_bf16 v[48:63], v[66:69], v[70:73], v[48:63]
	v_mfma_f32_32x32x16_bf16 v[32:47], v[74:77], v[70:73], v[32:47]
	s_waitcnt lgkmcnt(0)
	v_mfma_f32_32x32x16_bf16 v[16:31], v[66:69], v[154:157], v[16:31]
	v_mfma_f32_32x32x16_bf16 v[0:15], v[74:77], v[154:157], v[0:15]
	ds_read_b128 v[66:69], v87 offset:32768
	ds_read_b128 v[70:73], v86
	ds_read_b128 v[74:77], v87 offset:36864
	ds_read_b128 v[150:153], v86 offset:4096
	s_waitcnt lgkmcnt(1)
	v_mfma_f32_32x32x16_bf16 v[48:63], v[66:69], v[70:73], v[48:63]
	v_mfma_f32_32x32x16_bf16 v[32:47], v[74:77], v[70:73], v[32:47]
	s_waitcnt lgkmcnt(0)
	v_mfma_f32_32x32x16_bf16 v[16:31], v[66:69], v[150:153], v[16:31]
	v_mfma_f32_32x32x16_bf16 v[0:15], v[74:77], v[150:153], v[0:15]
	ds_read_b128 v[70:73], v89 offset:32768
	ds_read_b128 v[66:69], v88
	ds_read_b128 v[74:77], v89 offset:36864
	ds_read_b128 v[82:85], v88 offset:4096
	s_waitcnt lgkmcnt(0)
	s_barrier
	s_waitcnt lgkmcnt(0)
	v_mfma_f32_32x32x16_bf16 v[48:63], v[70:73], v[66:69], v[48:63]
	v_mfma_f32_32x32x16_bf16 v[32:47], v[74:77], v[66:69], v[32:47]
	v_lshl_or_b32 v69, v80, 6, v81
	v_add_u32_e32 v66, s2, v69
	v_cmp_gt_i32_e32 vcc, s69, v66
	v_ashrrev_i32_e32 v67, 31, v66
	v_mov_b32_e32 v68, 0
	v_mfma_f32_32x32x16_bf16 v[16:31], v[70:73], v[82:85], v[16:31]
	v_mov_b32_e32 v70, 0
	v_mfma_f32_32x32x16_bf16 v[0:15], v[74:77], v[82:85], v[0:15]
	s_and_saveexec_b64 s[0:1], vcc
	s_cbranch_execz .LBB0_749
	v_lshl_add_u64 v[70:71], v[66:67], 2, s[76:77]
	v_mov_b32_e32 v70, v184
	v_fmamk_f32 v70, v70, 0x3a800000, v188
	v_mul_f32_e32 v71, 0x4b800000, v70
	v_cmp_gt_f32_e32 vcc, s82, v70
	s_nop 1
	v_cndmask_b32_e32 v70, v70, v71, vcc
	v_rsq_f32_e32 v70, v70
	s_nop 0
	v_mul_f32_e32 v71, 0x45800000, v70
	v_cndmask_b32_e32 v70, v70, v71, vcc
